# s_sleep 2 before the counted wait in every GEMM K-loop load segment (waves park in sleep instead of at waitcnt/barrier)
# baseline (speedup 1.0000x reference)
; template <class Epi, class Sched, bool ALIGN_EPI = false, bool SP2 = false>
; __device__ __forceinline__ void gemm_phase(PG8_LAS unsigned char* lds, const Gemm g, const Sched& S, const Epi& E) {
;     ...
;         const bool has_next = S.next(ui + 1, nxt);
;         const char* nA = has_next ? (const char*)g.A + (size_t)nxt.pm * tstepA : cA; const char* nB = has_next ? (const char*)g.Bt + (size_t)nxt.pn * tstepB : cB;
.LBB0_160:
	s_ashr_i32 s55, s54, 31
	s_lshl_b64 s[2:3], s[54:55], 15
	v_readlane_b32 s8, v255, 15
	s_add_u32 s12, s8, s2
	v_readlane_b32 s2, v255, 16
	s_addc_u32 s13, s2, s3
	s_ashr_i32 s49, s48, 31
	s_lshl_b64 s[2:3], s[48:49], 19
	v_readlane_b32 s8, v255, 29
	s_add_u32 s46, s8, s2
	v_readlane_b32 s2, v255, 40
	s_addc_u32 s47, s2, s3
	s_add_u32 s28, s24, 0x800000
	s_addc_u32 s29, s25, 0
	s_add_u32 s42, s24, 0xc00000
	s_addc_u32 s43, s25, 0
	s_add_i32 s55, 0, 0x10000
	s_and_b64 s[2:3], s[30:31], exec
	s_cselect_b32 s27, s13, s25
	s_cselect_b32 s44, s12, s24
	s_add_i32 vcc_hi, 0, 0x14000
	v_add_u32_e32 v142, s55, v97
	v_add_u32_e32 v143, vcc_hi, v97
	ds_read_b128 v[0:3], v142
	ds_read_b128 v[4:7], v142 offset:1024
	ds_read_b128 v[8:11], v142 offset:2048
	ds_read_b128 v[12:15], v142 offset:3072
	ds_read_b128 v[16:19], v143
	s_waitcnt lgkmcnt(0)
	ds_read_b128 v[20:23], v143 offset:1024
	ds_read_b128 v[24:27], v143 offset:2048
	ds_read_b128 v[28:31], v143 offset:3072
	v_writelane_b32 v255, s30, 33
	s_and_b64 s[2:3], s[30:31], exec
	s_cselect_b32 s45, s47, s1
	v_writelane_b32 v255, s31, 34
	s_cselect_b32 s49, s46, s0
	s_add_u32 s2, s24, 0x404000
	s_addc_u32 s3, s25, 0
	s_add_i32 s50, s22, 0xc000
	v_lshl_add_u64 v[64:65], s[2:3], 0, v[130:131]
	s_mov_b32 m0, s50
	s_add_i32 s51, s22, 0xe000
	ds_read_b128 v[32:35], v161
	ds_read_b128 v[36:39], v161 offset:1024
	ds_read_b128 v[40:43], v161 offset:2048
	ds_read_b128 v[44:47], v161 offset:3072
	ds_read_b128 v[48:51], v161 offset:4096
	ds_read_b128 v[52:55], v161 offset:5120
	ds_read_b128 v[56:59], v161 offset:6144
	ds_read_b128 v[60:63], v161 offset:7168
	global_load_lds_dwordx4 v[64:65], off
	v_lshl_add_u64 v[64:65], s[2:3], 0, v[134:135]
	s_mov_b32 m0, s51
	s_nop 0
	global_load_lds_dwordx4 v[64:65], off
	s_sleep 2
	s_waitcnt vmcnt(8)
	s_waitcnt lgkmcnt(0)
	s_barrier
	s_setprio 1
	s_waitcnt lgkmcnt(0)
	v_mfma_f32_16x16x32_bf16 v[64:67], v[0:3], v[32:35], 0
	v_mfma_f32_16x16x32_bf16 v[68:71], v[8:11], v[32:35], 0
	v_mfma_f32_16x16x32_bf16 v[72:75], v[0:3], v[40:43], 0
	v_mfma_f32_16x16x32_bf16 v[76:79], v[8:11], v[40:43], 0
	v_mfma_f32_16x16x32_bf16 v[80:83], v[0:3], v[48:51], 0
	v_mfma_f32_16x16x32_bf16 v[84:87], v[8:11], v[48:51], 0
	v_mfma_f32_16x16x32_bf16 v[88:91], v[0:3], v[56:59], 0
	v_mfma_f32_16x16x32_bf16 v[92:95], v[8:11], v[56:59], 0
	v_mfma_f32_16x16x32_bf16 v[64:67], v[4:7], v[36:39], v[64:67]
	v_mfma_f32_16x16x32_bf16 v[68:71], v[12:15], v[36:39], v[68:71]
	v_mfma_f32_16x16x32_bf16 v[72:75], v[4:7], v[44:47], v[72:75]
	v_mfma_f32_16x16x32_bf16 v[76:79], v[12:15], v[44:47], v[76:79]
	v_mfma_f32_16x16x32_bf16 v[80:83], v[4:7], v[52:55], v[80:83]
	v_mfma_f32_16x16x32_bf16 v[84:87], v[12:15], v[52:55], v[84:87]
	v_mfma_f32_16x16x32_bf16 v[88:91], v[4:7], v[60:63], v[88:91]
	v_mfma_f32_16x16x32_bf16 v[98:101], v[12:15], v[60:63], v[92:95]
	s_setprio 0
	s_setprio 1
	v_mfma_f32_16x16x32_bf16 v[92:95], v[16:19], v[32:35], 0
	v_mfma_f32_16x16x32_bf16 v[32:35], v[24:27], v[32:35], 0
	v_mfma_f32_16x16x32_bf16 v[106:109], v[20:23], v[36:39], v[92:95]
	v_mfma_f32_16x16x32_bf16 v[32:35], v[28:31], v[36:39], v[32:35]
	v_mfma_f32_16x16x32_bf16 v[36:39], v[16:19], v[40:43], 0
	v_mfma_f32_16x16x32_bf16 v[40:43], v[24:27], v[40:43], 0
	v_mfma_f32_16x16x32_bf16 v[36:39], v[20:23], v[44:47], v[36:39]
	v_mfma_f32_16x16x32_bf16 v[40:43], v[28:31], v[44:47], v[40:43]
	v_mfma_f32_16x16x32_bf16 v[44:47], v[16:19], v[48:51], 0
	v_mfma_f32_16x16x32_bf16 v[48:51], v[24:27], v[48:51], 0
	v_mfma_f32_16x16x32_bf16 v[44:47], v[20:23], v[52:55], v[44:47]
	v_mfma_f32_16x16x32_bf16 v[48:51], v[28:31], v[52:55], v[48:51]
	v_mfma_f32_16x16x32_bf16 v[52:55], v[16:19], v[56:59], 0
	v_mfma_f32_16x16x32_bf16 v[56:59], v[24:27], v[56:59], 0
	v_mfma_f32_16x16x32_bf16 v[52:55], v[20:23], v[60:63], v[52:55]
	v_mfma_f32_16x16x32_bf16 v[56:59], v[28:31], v[60:63], v[56:59]
	s_setprio 0
	s_barrier
	v_lshl_add_u64 v[158:159], s[0:1], 0, v[132:133]
	s_mov_b64 s[2:3], 0x100
	s_add_i32 s55, s55, s10
	v_lshl_add_u64 v[144:145], v[158:159], 0, s[2:3]
	s_mov_b32 m0, s55
	v_lshl_add_u64 v[178:179], s[0:1], 0, v[136:137]
	s_add_i32 vcc_lo, s55, 0x2000
	ds_read_b128 v[60:63], v161 offset:16384
	ds_read_b128 v[92:95], v161 offset:17408
	ds_read_b128 v[102:105], v161 offset:18432
	ds_read_b128 v[110:113], v161 offset:19456
	ds_read_b128 v[114:117], v161 offset:20480
	ds_read_b128 v[118:121], v161 offset:21504
	ds_read_b128 v[122:125], v161 offset:22528
	ds_read_b128 v[126:129], v161 offset:23552
	global_load_lds_dwordx4 v[144:145], off
	v_lshl_add_u64 v[144:145], v[178:179], 0, s[2:3]
	s_add_u32 s2, s0, 0x40100
	s_mov_b32 m0, vcc_lo
	s_addc_u32 s3, s1, 0
	s_add_i32 vcc_hi, vcc_hi, s10
	global_load_lds_dwordx4 v[144:145], off
	v_lshl_add_u64 v[144:145], s[2:3], 0, v[132:133]
	s_mov_b32 m0, vcc_hi
	s_add_i32 s56, vcc_hi, 0x2000
	global_load_lds_dwordx4 v[144:145], off
	v_lshl_add_u64 v[144:145], s[2:3], 0, v[136:137]
	s_mov_b32 m0, s56
	s_nop 0
	global_load_lds_dwordx4 v[144:145], off
	v_lshl_add_u64 v[144:145], s[28:29], 0, v[130:131]
	s_mov_b32 m0, s22
	s_nop 0
	global_load_lds_dwordx4 v[144:145], off
	v_lshl_add_u64 v[144:145], s[28:29], 0, v[134:135]
	s_mov_b32 m0, s23
	s_nop 0
	global_load_lds_dwordx4 v[144:145], off
	s_sleep 2
	s_waitcnt vmcnt(8)
	s_waitcnt lgkmcnt(0)
	s_barrier
	s_setprio 1
	s_waitcnt lgkmcnt(0)
	v_mfma_f32_16x16x32_bf16 v[144:147], v[0:3], v[60:63], 0
	v_mfma_f32_16x16x32_bf16 v[154:157], v[0:3], v[102:105], 0
	v_mfma_f32_16x16x32_bf16 v[166:169], v[0:3], v[114:117], 0
	v_mfma_f32_16x16x32_bf16 v[0:3], v[0:3], v[122:125], 0
	v_mfma_f32_16x16x32_bf16 v[146:149], v[4:7], v[92:95], v[144:147]
	v_mfma_f32_16x16x32_bf16 v[154:157], v[4:7], v[110:113], v[154:157]
	v_mfma_f32_16x16x32_bf16 v[166:169], v[4:7], v[118:121], v[166:169]
	v_mfma_f32_16x16x32_bf16 v[0:3], v[4:7], v[126:129], v[0:3]
	v_mfma_f32_16x16x32_bf16 v[4:7], v[8:11], v[122:125], 0
	v_mfma_f32_16x16x32_bf16 v[150:153], v[8:11], v[60:63], 0
	v_mfma_f32_16x16x32_bf16 v[162:165], v[8:11], v[102:105], 0
	v_mfma_f32_16x16x32_bf16 v[170:173], v[8:11], v[114:117], 0
	v_mfma_f32_16x16x32_bf16 v[4:7], v[12:15], v[126:129], v[4:7]
	v_mfma_f32_16x16x32_bf16 v[150:153], v[12:15], v[92:95], v[150:153]
	v_mfma_f32_16x16x32_bf16 v[162:165], v[12:15], v[110:113], v[162:165]
	v_mfma_f32_16x16x32_bf16 v[170:173], v[12:15], v[118:121], v[170:173]
	s_setprio 0
	s_setprio 1
	v_mfma_f32_16x16x32_bf16 v[12:15], v[24:27], v[60:63], 0
	v_mfma_f32_16x16x32_bf16 v[174:177], v[28:31], v[92:95], v[12:15]
	v_mfma_f32_16x16x32_bf16 v[12:15], v[16:19], v[102:105], 0
	v_mfma_f32_16x16x32_bf16 v[180:183], v[20:23], v[110:113], v[12:15]
	v_mfma_f32_16x16x32_bf16 v[12:15], v[24:27], v[102:105], 0
	v_mfma_f32_16x16x32_bf16 v[184:187], v[28:31], v[110:113], v[12:15]
	v_mfma_f32_16x16x32_bf16 v[12:15], v[16:19], v[114:117], 0
	v_mfma_f32_16x16x32_bf16 v[188:191], v[20:23], v[118:121], v[12:15]
	v_mfma_f32_16x16x32_bf16 v[12:15], v[24:27], v[114:117], 0
	v_mfma_f32_16x16x32_bf16 v[8:11], v[16:19], v[60:63], 0
	v_mfma_f32_16x16x32_bf16 v[192:195], v[28:31], v[118:121], v[12:15]
	v_mfma_f32_16x16x32_bf16 v[12:15], v[16:19], v[122:125], 0
	v_mfma_f32_16x16x32_bf16 v[8:11], v[20:23], v[92:95], v[8:11]
	v_mfma_f32_16x16x32_bf16 v[196:199], v[20:23], v[126:129], v[12:15]
	v_mfma_f32_16x16x32_bf16 v[12:15], v[24:27], v[122:125], 0
	v_mfma_f32_16x16x32_bf16 v[200:203], v[28:31], v[126:129], v[12:15]
	s_setprio 0
	s_barrier
	s_add_i32 s30, 0, 0x18000
	s_add_i32 s57, 0, 0x1c000
	v_add_u32_e32 v144, s30, v97
	v_add_u32_e32 v145, s57, v97
	s_nop 0
	ds_read_b128 v[12:15], v144
	ds_read_b128 v[16:19], v144 offset:1024
	ds_read_b128 v[24:27], v144 offset:2048
	ds_read_b128 v[204:207], v144 offset:3072
	ds_read_b128 v[208:211], v145
	ds_read_b128 v[212:215], v145 offset:1024
	ds_read_b128 v[216:219], v145 offset:2048
	ds_read_b128 v[220:223], v145 offset:3072
	s_add_u32 s2, s24, 0x804000
	s_addc_u32 s3, s25, 0
	s_mov_b32 m0, s39
	v_lshl_add_u64 v[92:93], s[2:3], 0, v[130:131]
	ds_read_b128 v[20:23], v161 offset:32768
	ds_read_b128 v[28:31], v161 offset:33792
	ds_read_b128 v[60:63], v161 offset:34816
	ds_read_b128 v[224:227], v161 offset:35840
	ds_read_b128 v[228:231], v161 offset:36864
	ds_read_b128 v[234:237], v161 offset:37888
	ds_read_b128 v[238:241], v161 offset:38912
	ds_read_b128 v[242:245], v161 offset:39936
	global_load_lds_dwordx4 v[92:93], off
	v_lshl_add_u64 v[92:93], s[2:3], 0, v[134:135]
	s_mov_b32 m0, s52
	s_nop 0
	global_load_lds_dwordx4 v[92:93], off
	s_sleep 2
	s_waitcnt vmcnt(8)
	s_waitcnt lgkmcnt(0)
	s_barrier
	s_setprio 1
	s_waitcnt lgkmcnt(0)
	v_mfma_f32_16x16x32_bf16 v[64:67], v[12:15], v[20:23], v[64:67]
	v_mfma_f32_16x16x32_bf16 v[126:129], v[16:19], v[28:31], v[64:67]
	v_mfma_f32_16x16x32_bf16 v[64:67], v[24:27], v[20:23], v[68:71]
	v_mfma_f32_16x16x32_bf16 v[118:121], v[204:207], v[28:31], v[64:67]
	v_mfma_f32_16x16x32_bf16 v[64:67], v[12:15], v[60:63], v[72:75]
	v_mfma_f32_16x16x32_bf16 v[110:113], v[16:19], v[224:227], v[64:67]
	v_mfma_f32_16x16x32_bf16 v[64:67], v[24:27], v[60:63], v[76:79]
	v_mfma_f32_16x16x32_bf16 v[102:105], v[204:207], v[224:227], v[64:67]
	v_mfma_f32_16x16x32_bf16 v[64:67], v[12:15], v[228:231], v[80:83]
	v_mfma_f32_16x16x32_bf16 v[92:95], v[16:19], v[234:237], v[64:67]
	v_mfma_f32_16x16x32_bf16 v[64:67], v[24:27], v[228:231], v[84:87]
	v_mfma_f32_16x16x32_bf16 v[84:87], v[204:207], v[234:237], v[64:67]
	v_mfma_f32_16x16x32_bf16 v[64:67], v[12:15], v[238:241], v[88:91]
	v_mfma_f32_16x16x32_bf16 v[76:79], v[16:19], v[242:245], v[64:67]
	v_mfma_f32_16x16x32_bf16 v[64:67], v[24:27], v[238:241], v[98:101]
	v_mfma_f32_16x16x32_bf16 v[68:71], v[204:207], v[242:245], v[64:67]
	s_setprio 0
	s_setprio 1
	v_mfma_f32_16x16x32_bf16 v[64:67], v[208:211], v[20:23], v[106:109]
	v_mfma_f32_16x16x32_bf16 v[20:23], v[216:219], v[20:23], v[32:35]
	v_mfma_f32_16x16x32_bf16 v[114:117], v[220:223], v[28:31], v[20:23]
	v_mfma_f32_16x16x32_bf16 v[20:23], v[208:211], v[60:63], v[36:39]
	v_mfma_f32_16x16x32_bf16 v[106:109], v[212:215], v[224:227], v[20:23]
	v_mfma_f32_16x16x32_bf16 v[20:23], v[216:219], v[60:63], v[40:43]
	v_mfma_f32_16x16x32_bf16 v[98:101], v[220:223], v[224:227], v[20:23]
	v_mfma_f32_16x16x32_bf16 v[20:23], v[208:211], v[228:231], v[44:47]
	v_mfma_f32_16x16x32_bf16 v[88:91], v[212:215], v[234:237], v[20:23]
	v_mfma_f32_16x16x32_bf16 v[20:23], v[216:219], v[228:231], v[48:51]
	v_mfma_f32_16x16x32_bf16 v[80:83], v[220:223], v[234:237], v[20:23]
	v_mfma_f32_16x16x32_bf16 v[20:23], v[208:211], v[238:241], v[52:55]
	v_mfma_f32_16x16x32_bf16 v[72:75], v[212:215], v[242:245], v[20:23]
	v_mfma_f32_16x16x32_bf16 v[20:23], v[216:219], v[238:241], v[56:59]
	v_mfma_f32_16x16x32_bf16 v[122:125], v[212:215], v[28:31], v[64:67]
	v_mfma_f32_16x16x32_bf16 v[64:67], v[220:223], v[242:245], v[20:23]
	s_setprio 0
	s_barrier
; template <class Epi, class Sched, bool ALIGN_EPI = false, bool SP2 = false>
; __device__ __forceinline__ void gemm_phase(PG8_LAS unsigned char* lds, const Gemm g, const Sched& S, const Epi& E) {
;     ...
;         for (int t = (Epi::PEEL ? 2 : 0); t < nt; t += 2) {
;             const bool last = (t == nt - 2);
;             const char* a1 = cA + (size_t)(t + 1) * kstepA;
;             const char* a2 = last ? nA : cA + (size_t)(t + 2) * kstepA; const char* b2 = last ? nB : cB + (size_t)(t + 2) * kstepB;
;             const char* a3 = a2 + kstepA; const char* b3 = b2 + kstepB;
	s_mov_b64 s[2:3], 0x180
	s_add_i32 s30, s30, s10
	s_nop 1
	v_lshl_add_u64 v[20:21], v[158:159], 0, s[2:3]
	s_mov_b32 m0, s30
	s_add_i32 s31, s30, 0x2000
	ds_read_b128 v[32:35], v161 offset:49152
	ds_read_b128 v[40:43], v161 offset:50176
	ds_read_b128 v[224:227], v161 offset:51200
	ds_read_b128 v[228:231], v161 offset:52224
	ds_read_b128 v[234:237], v161 offset:53248
	ds_read_b128 v[238:241], v161 offset:54272
	ds_read_b128 v[242:245], v161 offset:55296
	ds_read_b128 v[246:249], v161 offset:56320
	global_load_lds_dwordx4 v[20:21], off
	v_lshl_add_u64 v[20:21], v[178:179], 0, s[2:3]
	s_add_u32 s2, s0, 0x40180
	s_mov_b32 m0, s31
	s_addc_u32 s3, s1, 0
	s_add_i32 s57, s57, s10
	global_load_lds_dwordx4 v[20:21], off
	v_lshl_add_u64 v[20:21], s[2:3], 0, v[132:133]
	s_mov_b32 m0, s57
	s_add_i32 s96, s57, 0x2000
	global_load_lds_dwordx4 v[20:21], off
	v_lshl_add_u64 v[20:21], s[2:3], 0, v[136:137]
	s_mov_b32 m0, s96
	s_nop 0
	global_load_lds_dwordx4 v[20:21], off
	v_lshl_add_u64 v[20:21], s[42:43], 0, v[130:131]
	s_mov_b32 m0, s11
	s_nop 0
	global_load_lds_dwordx4 v[20:21], off
	v_lshl_add_u64 v[20:21], s[42:43], 0, v[134:135]
	s_mov_b32 m0, s19
	s_nop 0
	global_load_lds_dwordx4 v[20:21], off
	s_sleep 2
	s_waitcnt vmcnt(8)
	s_waitcnt lgkmcnt(0)
	s_barrier
	s_setprio 1
	s_waitcnt lgkmcnt(0)
	v_mfma_f32_16x16x32_bf16 v[20:23], v[12:15], v[32:35], v[146:149]
	v_mfma_f32_16x16x32_bf16 v[60:63], v[16:19], v[40:43], v[20:23]
	v_mfma_f32_16x16x32_bf16 v[20:23], v[24:27], v[32:35], v[150:153]
	v_mfma_f32_16x16x32_bf16 v[52:55], v[204:207], v[40:43], v[20:23]
	v_mfma_f32_16x16x32_bf16 v[20:23], v[12:15], v[224:227], v[154:157]
	v_mfma_f32_16x16x32_bf16 v[44:47], v[16:19], v[228:231], v[20:23]
	v_mfma_f32_16x16x32_bf16 v[20:23], v[24:27], v[224:227], v[162:165]
	v_mfma_f32_16x16x32_bf16 v[36:39], v[204:207], v[228:231], v[20:23]
	v_mfma_f32_16x16x32_bf16 v[20:23], v[12:15], v[234:237], v[166:169]
	v_mfma_f32_16x16x32_bf16 v[0:3], v[12:15], v[242:245], v[0:3]
	v_mfma_f32_16x16x32_bf16 v[28:31], v[16:19], v[238:241], v[20:23]
	v_mfma_f32_16x16x32_bf16 v[20:23], v[24:27], v[234:237], v[170:173]
	v_mfma_f32_16x16x32_bf16 v[12:15], v[16:19], v[246:249], v[0:3]
	v_mfma_f32_16x16x32_bf16 v[0:3], v[24:27], v[242:245], v[4:7]
	v_mfma_f32_16x16x32_bf16 v[20:23], v[204:207], v[238:241], v[20:23]
	v_mfma_f32_16x16x32_bf16 v[4:7], v[204:207], v[246:249], v[0:3]
	s_setprio 0
	s_setprio 1
	v_mfma_f32_16x16x32_bf16 v[0:3], v[208:211], v[32:35], v[8:11]
	v_mfma_f32_16x16x32_bf16 v[56:59], v[212:215], v[40:43], v[0:3]
	v_mfma_f32_16x16x32_bf16 v[0:3], v[216:219], v[32:35], v[174:177]
	v_mfma_f32_16x16x32_bf16 v[48:51], v[220:223], v[40:43], v[0:3]
	v_mfma_f32_16x16x32_bf16 v[0:3], v[208:211], v[224:227], v[180:183]
	v_mfma_f32_16x16x32_bf16 v[40:43], v[212:215], v[228:231], v[0:3]
	v_mfma_f32_16x16x32_bf16 v[0:3], v[216:219], v[224:227], v[184:187]
	v_mfma_f32_16x16x32_bf16 v[32:35], v[220:223], v[228:231], v[0:3]
	v_mfma_f32_16x16x32_bf16 v[0:3], v[208:211], v[234:237], v[188:191]
	v_mfma_f32_16x16x32_bf16 v[24:27], v[212:215], v[238:241], v[0:3]
	v_mfma_f32_16x16x32_bf16 v[0:3], v[216:219], v[234:237], v[192:195]
	v_mfma_f32_16x16x32_bf16 v[16:19], v[220:223], v[238:241], v[0:3]
	v_mfma_f32_16x16x32_bf16 v[0:3], v[208:211], v[242:245], v[196:199]
	v_mfma_f32_16x16x32_bf16 v[8:11], v[212:215], v[246:249], v[0:3]
	v_mfma_f32_16x16x32_bf16 v[0:3], v[216:219], v[242:245], v[200:203]
	v_mfma_f32_16x16x32_bf16 v[0:3], v[220:223], v[246:249], v[0:3]
	s_setprio 0
	s_barrier
	s_add_u32 s3, s0, 0x200
	s_addc_u32 s2, s1, 0
	s_add_u32 s0, s24, 0xc04000
	s_addc_u32 s1, s25, 0
	s_mov_b32 s18, 0
.LBB0_161:
	ds_read_b128 v[146:149], v142
	ds_read_b128 v[150:153], v142 offset:1024
	ds_read_b128 v[154:157], v142 offset:2048
	ds_read_b128 v[162:165], v142 offset:3072
	ds_read_b128 v[166:169], v143
	ds_read_b128 v[170:173], v143 offset:1024
	ds_read_b128 v[174:177], v143 offset:2048
	ds_read_b128 v[180:183], v143 offset:3072
	s_add_u32 s8, s0, 0x3fc000
	s_addc_u32 s9, s1, 0
	s_cmp_eq_u32 s18, 12
	s_cselect_b32 s28, s44, s8
	s_cselect_b32 s29, s27, s9
	s_cselect_b32 s42, s49, s3
	s_cselect_b32 s43, s45, s2
	s_add_u32 s24, s28, 0x400000
	s_addc_u32 s25, s29, 0
	s_mov_b32 m0, s50
	v_lshl_add_u64 v[158:159], s[0:1], 0, v[140:141]
	ds_read_b128 v[184:187], v161
	ds_read_b128 v[188:191], v161 offset:1024
	ds_read_b128 v[192:195], v161 offset:2048
	ds_read_b128 v[196:199], v161 offset:3072
	ds_read_b128 v[200:203], v161 offset:4096
	ds_read_b128 v[204:207], v161 offset:5120
	ds_read_b128 v[208:211], v161 offset:6144
	ds_read_b128 v[212:215], v161 offset:7168
	global_load_lds_dwordx4 v[158:159], off
	v_lshl_add_u64 v[158:159], s[0:1], 0, v[138:139]
	s_mov_b32 m0, s51
	s_nop 0
	global_load_lds_dwordx4 v[158:159], off
	s_sleep 2
	s_waitcnt vmcnt(8)
	s_waitcnt lgkmcnt(0)
	s_barrier
	s_setprio 1
	s_waitcnt lgkmcnt(0)
	v_mfma_f32_16x16x32_bf16 v[126:129], v[146:149], v[184:187], v[126:129]
	v_mfma_f32_16x16x32_bf16 v[118:121], v[154:157], v[184:187], v[118:121]
	v_mfma_f32_16x16x32_bf16 v[110:113], v[146:149], v[192:195], v[110:113]
	v_mfma_f32_16x16x32_bf16 v[102:105], v[154:157], v[192:195], v[102:105]
	v_mfma_f32_16x16x32_bf16 v[92:95], v[146:149], v[200:203], v[92:95]
	v_mfma_f32_16x16x32_bf16 v[84:87], v[154:157], v[200:203], v[84:87]
	v_mfma_f32_16x16x32_bf16 v[76:79], v[146:149], v[208:211], v[76:79]
	v_mfma_f32_16x16x32_bf16 v[68:71], v[154:157], v[208:211], v[68:71]
	v_mfma_f32_16x16x32_bf16 v[126:129], v[150:153], v[188:191], v[126:129]
	v_mfma_f32_16x16x32_bf16 v[118:121], v[162:165], v[188:191], v[118:121]
	v_mfma_f32_16x16x32_bf16 v[110:113], v[150:153], v[196:199], v[110:113]
	v_mfma_f32_16x16x32_bf16 v[102:105], v[162:165], v[196:199], v[102:105]
	v_mfma_f32_16x16x32_bf16 v[92:95], v[150:153], v[204:207], v[92:95]
	v_mfma_f32_16x16x32_bf16 v[84:87], v[162:165], v[204:207], v[84:87]
	v_mfma_f32_16x16x32_bf16 v[76:79], v[150:153], v[212:215], v[76:79]
	v_mfma_f32_16x16x32_bf16 v[68:71], v[162:165], v[212:215], v[68:71]
	s_setprio 0
	s_setprio 1
	v_mfma_f32_16x16x32_bf16 v[122:125], v[166:169], v[184:187], v[122:125]
	v_mfma_f32_16x16x32_bf16 v[114:117], v[174:177], v[184:187], v[114:117]
	v_mfma_f32_16x16x32_bf16 v[106:109], v[166:169], v[192:195], v[106:109]
	v_mfma_f32_16x16x32_bf16 v[98:101], v[174:177], v[192:195], v[98:101]
	v_mfma_f32_16x16x32_bf16 v[88:91], v[166:169], v[200:203], v[88:91]
	v_mfma_f32_16x16x32_bf16 v[80:83], v[174:177], v[200:203], v[80:83]
	v_mfma_f32_16x16x32_bf16 v[72:75], v[166:169], v[208:211], v[72:75]
	v_mfma_f32_16x16x32_bf16 v[64:67], v[174:177], v[208:211], v[64:67]
	v_mfma_f32_16x16x32_bf16 v[122:125], v[170:173], v[188:191], v[122:125]
	v_mfma_f32_16x16x32_bf16 v[114:117], v[180:183], v[188:191], v[114:117]
	v_mfma_f32_16x16x32_bf16 v[106:109], v[170:173], v[196:199], v[106:109]
	v_mfma_f32_16x16x32_bf16 v[98:101], v[180:183], v[196:199], v[98:101]
	v_mfma_f32_16x16x32_bf16 v[88:91], v[170:173], v[204:207], v[88:91]
	v_mfma_f32_16x16x32_bf16 v[80:83], v[180:183], v[204:207], v[80:83]
	v_mfma_f32_16x16x32_bf16 v[72:75], v[170:173], v[212:215], v[72:75]
	v_mfma_f32_16x16x32_bf16 v[64:67], v[180:183], v[212:215], v[64:67]
	s_setprio 0
	s_barrier
	s_mov_b32 m0, s55
	v_lshl_add_u64 v[158:159], s[42:43], 0, v[132:133]
	s_add_u32 s8, s42, 0x40000
	ds_read_b128 v[184:187], v161 offset:16384
	ds_read_b128 v[188:191], v161 offset:17408
	ds_read_b128 v[192:195], v161 offset:18432
	ds_read_b128 v[196:199], v161 offset:19456
	ds_read_b128 v[200:203], v161 offset:20480
	ds_read_b128 v[204:207], v161 offset:21504
	ds_read_b128 v[208:211], v161 offset:22528
	ds_read_b128 v[212:215], v161 offset:23552
	global_load_lds_dwordx4 v[158:159], off
	v_lshl_add_u64 v[178:179], s[42:43], 0, v[136:137]
	s_mov_b32 m0, vcc_lo
	s_addc_u32 s9, s43, 0
	global_load_lds_dwordx4 v[178:179], off
	v_lshl_add_u64 v[216:217], s[8:9], 0, v[132:133]
	s_mov_b32 m0, vcc_hi
	s_nop 0
	global_load_lds_dwordx4 v[216:217], off
	v_lshl_add_u64 v[216:217], s[8:9], 0, v[136:137]
	s_mov_b32 m0, s56
	s_nop 0
	global_load_lds_dwordx4 v[216:217], off
	v_lshl_add_u64 v[216:217], s[28:29], 0, v[130:131]
	s_mov_b32 m0, s22
	s_nop 0
	global_load_lds_dwordx4 v[216:217], off
	v_lshl_add_u64 v[216:217], s[28:29], 0, v[134:135]
	s_mov_b32 m0, s23
	s_nop 0
	global_load_lds_dwordx4 v[216:217], off
	s_sleep 2
	s_waitcnt vmcnt(8)
	s_waitcnt lgkmcnt(0)
	s_barrier
	s_setprio 1
	s_waitcnt lgkmcnt(0)
	v_mfma_f32_16x16x32_bf16 v[60:63], v[146:149], v[184:187], v[60:63]
	v_mfma_f32_16x16x32_bf16 v[52:55], v[154:157], v[184:187], v[52:55]
	v_mfma_f32_16x16x32_bf16 v[44:47], v[146:149], v[192:195], v[44:47]
	v_mfma_f32_16x16x32_bf16 v[36:39], v[154:157], v[192:195], v[36:39]
	v_mfma_f32_16x16x32_bf16 v[28:31], v[146:149], v[200:203], v[28:31]
	v_mfma_f32_16x16x32_bf16 v[20:23], v[154:157], v[200:203], v[20:23]
	v_mfma_f32_16x16x32_bf16 v[12:15], v[146:149], v[208:211], v[12:15]
	v_mfma_f32_16x16x32_bf16 v[4:7], v[154:157], v[208:211], v[4:7]
	v_mfma_f32_16x16x32_bf16 v[60:63], v[150:153], v[188:191], v[60:63]
	v_mfma_f32_16x16x32_bf16 v[52:55], v[162:165], v[188:191], v[52:55]
	v_mfma_f32_16x16x32_bf16 v[44:47], v[150:153], v[196:199], v[44:47]
	v_mfma_f32_16x16x32_bf16 v[36:39], v[162:165], v[196:199], v[36:39]
	v_mfma_f32_16x16x32_bf16 v[28:31], v[150:153], v[204:207], v[28:31]
	v_mfma_f32_16x16x32_bf16 v[20:23], v[162:165], v[204:207], v[20:23]
	v_mfma_f32_16x16x32_bf16 v[12:15], v[150:153], v[212:215], v[12:15]
	v_mfma_f32_16x16x32_bf16 v[4:7], v[162:165], v[212:215], v[4:7]
	s_setprio 0
	s_setprio 1
	v_mfma_f32_16x16x32_bf16 v[56:59], v[166:169], v[184:187], v[56:59]
	v_mfma_f32_16x16x32_bf16 v[48:51], v[174:177], v[184:187], v[48:51]
	v_mfma_f32_16x16x32_bf16 v[40:43], v[166:169], v[192:195], v[40:43]
	v_mfma_f32_16x16x32_bf16 v[32:35], v[174:177], v[192:195], v[32:35]
	v_mfma_f32_16x16x32_bf16 v[24:27], v[166:169], v[200:203], v[24:27]
	v_mfma_f32_16x16x32_bf16 v[16:19], v[174:177], v[200:203], v[16:19]
	v_mfma_f32_16x16x32_bf16 v[8:11], v[166:169], v[208:211], v[8:11]
	v_mfma_f32_16x16x32_bf16 v[0:3], v[174:177], v[208:211], v[0:3]
	v_mfma_f32_16x16x32_bf16 v[56:59], v[170:173], v[188:191], v[56:59]
	v_mfma_f32_16x16x32_bf16 v[48:51], v[180:183], v[188:191], v[48:51]
	v_mfma_f32_16x16x32_bf16 v[40:43], v[170:173], v[196:199], v[40:43]
	v_mfma_f32_16x16x32_bf16 v[32:35], v[180:183], v[196:199], v[32:35]
	v_mfma_f32_16x16x32_bf16 v[24:27], v[170:173], v[204:207], v[24:27]
	v_mfma_f32_16x16x32_bf16 v[16:19], v[180:183], v[204:207], v[16:19]
	v_mfma_f32_16x16x32_bf16 v[8:11], v[170:173], v[212:215], v[8:11]
	v_mfma_f32_16x16x32_bf16 v[0:3], v[180:183], v[212:215], v[0:3]
	s_setprio 0
	s_barrier
	ds_read_b128 v[146:149], v144
	ds_read_b128 v[150:153], v144 offset:1024
	ds_read_b128 v[154:157], v144 offset:2048
	ds_read_b128 v[162:165], v144 offset:3072
	ds_read_b128 v[166:169], v145
	ds_read_b128 v[170:173], v145 offset:1024
	ds_read_b128 v[174:177], v145 offset:2048
	ds_read_b128 v[180:183], v145 offset:3072
	s_add_u32 s8, s28, 0x4000
	s_addc_u32 s9, s29, 0
	s_mov_b32 m0, s39
	v_lshl_add_u64 v[216:217], s[8:9], 0, v[130:131]
	ds_read_b128 v[184:187], v161 offset:32768
	ds_read_b128 v[188:191], v161 offset:33792
	ds_read_b128 v[192:195], v161 offset:34816
	ds_read_b128 v[196:199], v161 offset:35840
	ds_read_b128 v[200:203], v161 offset:36864
	ds_read_b128 v[204:207], v161 offset:37888
	ds_read_b128 v[208:211], v161 offset:38912
	ds_read_b128 v[212:215], v161 offset:39936
	global_load_lds_dwordx4 v[216:217], off
	v_lshl_add_u64 v[216:217], s[8:9], 0, v[134:135]
	s_mov_b32 m0, s52
	s_nop 0
	global_load_lds_dwordx4 v[216:217], off
	s_sleep 2
	s_waitcnt vmcnt(8)
	s_waitcnt lgkmcnt(0)
	s_barrier
	s_setprio 1
	s_waitcnt lgkmcnt(0)
	v_mfma_f32_16x16x32_bf16 v[126:129], v[146:149], v[184:187], v[126:129]
	v_mfma_f32_16x16x32_bf16 v[118:121], v[154:157], v[184:187], v[118:121]
	v_mfma_f32_16x16x32_bf16 v[110:113], v[146:149], v[192:195], v[110:113]
	v_mfma_f32_16x16x32_bf16 v[102:105], v[154:157], v[192:195], v[102:105]
	v_mfma_f32_16x16x32_bf16 v[92:95], v[146:149], v[200:203], v[92:95]
	v_mfma_f32_16x16x32_bf16 v[84:87], v[154:157], v[200:203], v[84:87]
	v_mfma_f32_16x16x32_bf16 v[76:79], v[146:149], v[208:211], v[76:79]
	v_mfma_f32_16x16x32_bf16 v[68:71], v[154:157], v[208:211], v[68:71]
	v_mfma_f32_16x16x32_bf16 v[126:129], v[150:153], v[188:191], v[126:129]
	v_mfma_f32_16x16x32_bf16 v[118:121], v[162:165], v[188:191], v[118:121]
	v_mfma_f32_16x16x32_bf16 v[110:113], v[150:153], v[196:199], v[110:113]
	v_mfma_f32_16x16x32_bf16 v[102:105], v[162:165], v[196:199], v[102:105]
	v_mfma_f32_16x16x32_bf16 v[92:95], v[150:153], v[204:207], v[92:95]
	v_mfma_f32_16x16x32_bf16 v[84:87], v[162:165], v[204:207], v[84:87]
	v_mfma_f32_16x16x32_bf16 v[76:79], v[150:153], v[212:215], v[76:79]
	v_mfma_f32_16x16x32_bf16 v[68:71], v[162:165], v[212:215], v[68:71]
	s_setprio 0
	s_setprio 1
	v_mfma_f32_16x16x32_bf16 v[122:125], v[166:169], v[184:187], v[122:125]
	v_mfma_f32_16x16x32_bf16 v[114:117], v[174:177], v[184:187], v[114:117]
	v_mfma_f32_16x16x32_bf16 v[106:109], v[166:169], v[192:195], v[106:109]
	v_mfma_f32_16x16x32_bf16 v[98:101], v[174:177], v[192:195], v[98:101]
	v_mfma_f32_16x16x32_bf16 v[88:91], v[166:169], v[200:203], v[88:91]
	v_mfma_f32_16x16x32_bf16 v[80:83], v[174:177], v[200:203], v[80:83]
	v_mfma_f32_16x16x32_bf16 v[72:75], v[166:169], v[208:211], v[72:75]
	v_mfma_f32_16x16x32_bf16 v[64:67], v[174:177], v[208:211], v[64:67]
	v_mfma_f32_16x16x32_bf16 v[122:125], v[170:173], v[188:191], v[122:125]
	v_mfma_f32_16x16x32_bf16 v[114:117], v[180:183], v[188:191], v[114:117]
	v_mfma_f32_16x16x32_bf16 v[106:109], v[170:173], v[196:199], v[106:109]
	v_mfma_f32_16x16x32_bf16 v[98:101], v[180:183], v[196:199], v[98:101]
	v_mfma_f32_16x16x32_bf16 v[88:91], v[170:173], v[204:207], v[88:91]
	v_mfma_f32_16x16x32_bf16 v[80:83], v[180:183], v[204:207], v[80:83]
	v_mfma_f32_16x16x32_bf16 v[72:75], v[170:173], v[212:215], v[72:75]
	v_mfma_f32_16x16x32_bf16 v[64:67], v[180:183], v[212:215], v[64:67]
	s_setprio 0
	s_barrier
; #define PG8_BAR __builtin_amdgcn_s_barrier()
; template <class Epi, class Sched, bool ALIGN_EPI = false, bool SP2 = false>
; __device__ __forceinline__ void gemm_phase(PG8_LAS unsigned char* lds, const Gemm g, const Sched& S, const Epi& E) {
;     ...
;             PG8_ITER(8);
;         }
;     ...
;         if constexpr (ALIGN_EPI) { if (wr == 0) PG8_BAR; }
	s_mov_b32 m0, s30
	v_lshl_add_u64 v[158:159], v[158:159], 0, s[36:37]
	s_add_u32 s8, s42, 0x40080
	ds_read_b128 v[184:187], v161 offset:49152
	ds_read_b128 v[188:191], v161 offset:50176
	ds_read_b128 v[192:195], v161 offset:51200
	ds_read_b128 v[196:199], v161 offset:52224
	ds_read_b128 v[200:203], v161 offset:53248
	ds_read_b128 v[204:207], v161 offset:54272
	ds_read_b128 v[208:211], v161 offset:55296
	ds_read_b128 v[212:215], v161 offset:56320
	global_load_lds_dwordx4 v[158:159], off
	v_lshl_add_u64 v[158:159], v[178:179], 0, s[36:37]
	s_mov_b32 m0, s31
	s_addc_u32 s9, s43, 0
	global_load_lds_dwordx4 v[158:159], off
	v_lshl_add_u64 v[158:159], s[8:9], 0, v[132:133]
	s_mov_b32 m0, s57
	s_nop 0
	global_load_lds_dwordx4 v[158:159], off
	v_lshl_add_u64 v[158:159], s[8:9], 0, v[136:137]
	s_mov_b32 m0, s96
	s_nop 0
	global_load_lds_dwordx4 v[158:159], off
	v_lshl_add_u64 v[158:159], s[24:25], 0, v[130:131]
	s_mov_b32 m0, s11
	s_nop 0
	global_load_lds_dwordx4 v[158:159], off
	v_lshl_add_u64 v[158:159], s[24:25], 0, v[134:135]
	s_mov_b32 m0, s19
	s_nop 0
	global_load_lds_dwordx4 v[158:159], off
	s_sleep 2
	s_waitcnt vmcnt(8)
	s_waitcnt lgkmcnt(0)
	s_barrier
	s_setprio 1
	s_waitcnt lgkmcnt(0)
	v_mfma_f32_16x16x32_bf16 v[60:63], v[146:149], v[184:187], v[60:63]
	v_mfma_f32_16x16x32_bf16 v[52:55], v[154:157], v[184:187], v[52:55]
	v_mfma_f32_16x16x32_bf16 v[44:47], v[146:149], v[192:195], v[44:47]
	v_mfma_f32_16x16x32_bf16 v[36:39], v[154:157], v[192:195], v[36:39]
	v_mfma_f32_16x16x32_bf16 v[28:31], v[146:149], v[200:203], v[28:31]
	v_mfma_f32_16x16x32_bf16 v[20:23], v[154:157], v[200:203], v[20:23]
	v_mfma_f32_16x16x32_bf16 v[12:15], v[146:149], v[208:211], v[12:15]
	v_mfma_f32_16x16x32_bf16 v[4:7], v[154:157], v[208:211], v[4:7]
	v_mfma_f32_16x16x32_bf16 v[60:63], v[150:153], v[188:191], v[60:63]
	v_mfma_f32_16x16x32_bf16 v[52:55], v[162:165], v[188:191], v[52:55]
	v_mfma_f32_16x16x32_bf16 v[44:47], v[150:153], v[196:199], v[44:47]
	v_mfma_f32_16x16x32_bf16 v[36:39], v[162:165], v[196:199], v[36:39]
	v_mfma_f32_16x16x32_bf16 v[28:31], v[150:153], v[204:207], v[28:31]
	v_mfma_f32_16x16x32_bf16 v[20:23], v[162:165], v[204:207], v[20:23]
	v_mfma_f32_16x16x32_bf16 v[12:15], v[150:153], v[212:215], v[12:15]
	v_mfma_f32_16x16x32_bf16 v[4:7], v[162:165], v[212:215], v[4:7]
	s_setprio 0
	s_setprio 1
	v_mfma_f32_16x16x32_bf16 v[56:59], v[166:169], v[184:187], v[56:59]
	v_mfma_f32_16x16x32_bf16 v[48:51], v[174:177], v[184:187], v[48:51]
	v_mfma_f32_16x16x32_bf16 v[40:43], v[166:169], v[192:195], v[40:43]
	v_mfma_f32_16x16x32_bf16 v[32:35], v[174:177], v[192:195], v[32:35]
	v_mfma_f32_16x16x32_bf16 v[24:27], v[166:169], v[200:203], v[24:27]
	v_mfma_f32_16x16x32_bf16 v[16:19], v[174:177], v[200:203], v[16:19]
	v_mfma_f32_16x16x32_bf16 v[8:11], v[166:169], v[208:211], v[8:11]
	v_mfma_f32_16x16x32_bf16 v[0:3], v[174:177], v[208:211], v[0:3]
	v_mfma_f32_16x16x32_bf16 v[56:59], v[170:173], v[188:191], v[56:59]
	v_mfma_f32_16x16x32_bf16 v[48:51], v[180:183], v[188:191], v[48:51]
	v_mfma_f32_16x16x32_bf16 v[40:43], v[170:173], v[196:199], v[40:43]
	v_mfma_f32_16x16x32_bf16 v[32:35], v[180:183], v[196:199], v[32:35]
	v_mfma_f32_16x16x32_bf16 v[24:27], v[170:173], v[204:207], v[24:27]
	v_mfma_f32_16x16x32_bf16 v[16:19], v[180:183], v[204:207], v[16:19]
	v_mfma_f32_16x16x32_bf16 v[8:11], v[170:173], v[212:215], v[8:11]
	v_mfma_f32_16x16x32_bf16 v[0:3], v[180:183], v[212:215], v[0:3]
	s_setprio 0
	s_barrier
	s_add_i32 s18, s18, 2
	s_add_u32 s3, s3, 0x100
	s_addc_u32 s2, s2, 0
	s_add_u32 s0, s0, 0x800000
	s_addc_u32 s1, s1, 0
	s_cmp_gt_u32 s18, 13
	s_cbranch_scc0 .LBB0_161
	v_readlane_b32 s0, v255, 45
	v_readlane_b32 s1, v255, 46
	s_and_b64 vcc, exec, s[0:1]
	s_cbranch_vccz .LBB0_164
	s_barrier

; template <class Epi, class Sched, bool ALIGN_EPI = false, bool SP2 = false>
; __device__ __forceinline__ void gemm_phase(PG8_LAS unsigned char* lds, const Gemm g, const Sched& S, const Epi& E) {
;     ...
;         const bool has_next = S.next(ui + 1, nxt);
;         const char* nA = has_next ? (const char*)g.A + (size_t)nxt.pm * tstepA : cA; const char* nB = has_next ? (const char*)g.Bt + (size_t)nxt.pn * tstepB : cB;
.LBB0_249:
	s_ashr_i32 s49, s48, 31
	s_lshl_b64 s[2:3], s[48:49], 15
	v_readlane_b32 s11, v255, 15
	s_add_u32 s50, s11, s2
	v_readlane_b32 s2, v255, 16
	s_addc_u32 s51, s2, s3
	s_ashr_i32 s47, s46, 31
	s_lshl_b64 s[2:3], s[46:47], 19
	s_add_u32 s52, s38, s2
	s_addc_u32 s53, s19, s3
	s_add_u32 s28, s42, 0x800000
	s_addc_u32 s29, s43, 0
	s_add_u32 s44, s42, 0xc00000
	s_addc_u32 s45, s43, 0
	s_add_i32 s99, 0, 0x10000
	s_and_b64 s[2:3], s[40:41], exec
	s_cselect_b32 s27, s51, s43
	s_cselect_b32 s47, s50, s42
	s_add_i32 vcc_hi, 0, 0x14000
	v_add_u32_e32 v130, s99, v97
	v_add_u32_e32 v131, vcc_hi, v97
	ds_read_b128 v[0:3], v130
	ds_read_b128 v[4:7], v130 offset:1024
	ds_read_b128 v[8:11], v130 offset:2048
	ds_read_b128 v[12:15], v130 offset:3072
	ds_read_b128 v[16:19], v131
	s_waitcnt lgkmcnt(0)
	ds_read_b128 v[20:23], v131 offset:1024
	ds_read_b128 v[24:27], v131 offset:2048
	ds_read_b128 v[28:31], v131 offset:3072
	s_and_b64 s[2:3], s[40:41], exec
	s_cselect_b32 s49, s53, s25
	s_cselect_b32 s54, s52, s24
	s_add_u32 s2, s42, 0x404000
	s_addc_u32 s3, s43, 0
	s_add_i32 s55, s22, 0xc000
	v_lshl_add_u64 v[64:65], s[2:3], 0, v[134:135]
	s_mov_b32 m0, s55
	s_add_i32 s98, s22, 0xe000
	ds_read_b128 v[32:35], v151
	ds_read_b128 v[36:39], v151 offset:1024
	ds_read_b128 v[40:43], v151 offset:2048
	ds_read_b128 v[44:47], v151 offset:3072
	ds_read_b128 v[48:51], v151 offset:4096
	ds_read_b128 v[52:55], v151 offset:5120
	ds_read_b128 v[56:59], v151 offset:6144
	ds_read_b128 v[60:63], v151 offset:7168
	global_load_lds_dwordx4 v[64:65], off
	v_lshl_add_u64 v[64:65], s[2:3], 0, v[138:139]
	s_mov_b32 m0, s98
	s_nop 0
	global_load_lds_dwordx4 v[64:65], off
	s_sleep 2
	s_waitcnt vmcnt(8)
	s_waitcnt lgkmcnt(0)
	s_barrier
	s_setprio 1
	s_waitcnt lgkmcnt(0)
	v_mfma_f32_16x16x32_bf16 v[84:87], v[8:11], v[48:51], 0
	v_mfma_f32_16x16x32_bf16 v[88:91], v[12:15], v[52:55], v[84:87]
	v_mfma_f32_16x16x32_bf16 v[84:87], v[0:3], v[56:59], 0
	v_mfma_f32_16x16x32_bf16 v[64:67], v[0:3], v[32:35], 0
	v_mfma_f32_16x16x32_bf16 v[68:71], v[8:11], v[32:35], 0
	v_mfma_f32_16x16x32_bf16 v[72:75], v[0:3], v[40:43], 0
	v_mfma_f32_16x16x32_bf16 v[76:79], v[8:11], v[40:43], 0
	v_mfma_f32_16x16x32_bf16 v[80:83], v[0:3], v[48:51], 0
	v_mfma_f32_16x16x32_bf16 v[92:95], v[4:7], v[60:63], v[84:87]
	v_mfma_f32_16x16x32_bf16 v[84:87], v[8:11], v[56:59], 0
	v_mfma_f32_16x16x32_bf16 v[64:67], v[4:7], v[36:39], v[64:67]
	v_mfma_f32_16x16x32_bf16 v[68:71], v[12:15], v[36:39], v[68:71]
	v_mfma_f32_16x16x32_bf16 v[72:75], v[4:7], v[44:47], v[72:75]
	v_mfma_f32_16x16x32_bf16 v[76:79], v[12:15], v[44:47], v[76:79]
	v_mfma_f32_16x16x32_bf16 v[80:83], v[4:7], v[52:55], v[80:83]
	v_mfma_f32_16x16x32_bf16 v[106:109], v[12:15], v[60:63], v[84:87]
	s_setprio 0
	s_setprio 1
	v_mfma_f32_16x16x32_bf16 v[84:87], v[16:19], v[32:35], 0
	v_mfma_f32_16x16x32_bf16 v[32:35], v[24:27], v[32:35], 0
	v_mfma_f32_16x16x32_bf16 v[110:113], v[20:23], v[36:39], v[84:87]
	v_mfma_f32_16x16x32_bf16 v[32:35], v[28:31], v[36:39], v[32:35]
	v_mfma_f32_16x16x32_bf16 v[36:39], v[16:19], v[40:43], 0
	v_mfma_f32_16x16x32_bf16 v[40:43], v[24:27], v[40:43], 0
	v_mfma_f32_16x16x32_bf16 v[36:39], v[20:23], v[44:47], v[36:39]
	v_mfma_f32_16x16x32_bf16 v[40:43], v[28:31], v[44:47], v[40:43]
	v_mfma_f32_16x16x32_bf16 v[44:47], v[16:19], v[48:51], 0
	v_mfma_f32_16x16x32_bf16 v[48:51], v[24:27], v[48:51], 0
	v_mfma_f32_16x16x32_bf16 v[44:47], v[20:23], v[52:55], v[44:47]
	v_mfma_f32_16x16x32_bf16 v[48:51], v[28:31], v[52:55], v[48:51]
	v_mfma_f32_16x16x32_bf16 v[52:55], v[16:19], v[56:59], 0
	v_mfma_f32_16x16x32_bf16 v[56:59], v[24:27], v[56:59], 0
	v_mfma_f32_16x16x32_bf16 v[52:55], v[20:23], v[60:63], v[52:55]
	v_mfma_f32_16x16x32_bf16 v[56:59], v[28:31], v[60:63], v[56:59]
	s_setprio 0
	s_barrier
	v_lshl_add_u64 v[176:177], s[24:25], 0, v[136:137]
	s_mov_b64 s[2:3], 0x100
	s_add_i32 s99, s99, s10
	v_lshl_add_u64 v[132:133], v[176:177], 0, s[2:3]
	s_mov_b32 m0, s99
	v_lshl_add_u64 v[178:179], s[24:25], 0, v[140:141]
	s_add_i32 vcc_lo, s99, 0x2000
	ds_read_b128 v[60:63], v151 offset:16384
	ds_read_b128 v[84:87], v151 offset:17408
	ds_read_b128 v[98:101], v151 offset:18432
	ds_read_b128 v[102:105], v151 offset:19456
	ds_read_b128 v[114:117], v151 offset:20480
	ds_read_b128 v[118:121], v151 offset:21504
	ds_read_b128 v[122:125], v151 offset:22528
	ds_read_b128 v[126:129], v151 offset:23552
	global_load_lds_dwordx4 v[132:133], off
	v_lshl_add_u64 v[132:133], v[178:179], 0, s[2:3]
	s_add_u32 s2, s24, 0x40100
	s_mov_b32 m0, vcc_lo
	s_addc_u32 s3, s25, 0
	s_add_i32 vcc_hi, vcc_hi, s10
	global_load_lds_dwordx4 v[132:133], off
	v_lshl_add_u64 v[132:133], s[2:3], 0, v[136:137]
	s_mov_b32 m0, vcc_hi
	s_add_i32 s30, vcc_hi, 0x2000
	global_load_lds_dwordx4 v[132:133], off
	v_lshl_add_u64 v[132:133], s[2:3], 0, v[140:141]
	s_mov_b32 m0, s30
	s_mov_b64 s[34:35], 0x100
	global_load_lds_dwordx4 v[132:133], off
	v_lshl_add_u64 v[132:133], s[28:29], 0, v[134:135]
	s_mov_b32 m0, s22
	s_nop 0
	global_load_lds_dwordx4 v[132:133], off
	v_lshl_add_u64 v[132:133], s[28:29], 0, v[138:139]
	s_mov_b32 m0, s23
	s_nop 0
	global_load_lds_dwordx4 v[132:133], off
	s_sleep 2
	s_waitcnt vmcnt(8)
	s_waitcnt lgkmcnt(0)
	s_barrier
	s_setprio 1
	s_waitcnt lgkmcnt(0)
	v_mfma_f32_16x16x32_bf16 v[146:149], v[0:3], v[60:63], 0
	v_mfma_f32_16x16x32_bf16 v[156:159], v[0:3], v[98:101], 0
	v_mfma_f32_16x16x32_bf16 v[164:167], v[0:3], v[114:117], 0
	v_mfma_f32_16x16x32_bf16 v[0:3], v[0:3], v[122:125], 0
	v_mfma_f32_16x16x32_bf16 v[146:149], v[4:7], v[84:87], v[146:149]
	v_mfma_f32_16x16x32_bf16 v[156:159], v[4:7], v[102:105], v[156:159]
	v_mfma_f32_16x16x32_bf16 v[164:167], v[4:7], v[118:121], v[164:167]
	v_mfma_f32_16x16x32_bf16 v[0:3], v[4:7], v[126:129], v[0:3]
	v_mfma_f32_16x16x32_bf16 v[4:7], v[8:11], v[122:125], 0
	v_mfma_f32_16x16x32_bf16 v[152:155], v[8:11], v[60:63], 0
	v_mfma_f32_16x16x32_bf16 v[160:163], v[8:11], v[98:101], 0
	v_mfma_f32_16x16x32_bf16 v[168:171], v[8:11], v[114:117], 0
	v_mfma_f32_16x16x32_bf16 v[8:11], v[12:15], v[126:129], v[4:7]
	v_mfma_f32_16x16x32_bf16 v[152:155], v[12:15], v[84:87], v[152:155]
	v_mfma_f32_16x16x32_bf16 v[160:163], v[12:15], v[102:105], v[160:163]
	v_mfma_f32_16x16x32_bf16 v[168:171], v[12:15], v[118:121], v[168:171]
	s_setprio 0
	s_setprio 1
	v_mfma_f32_16x16x32_bf16 v[4:7], v[16:19], v[60:63], 0
	v_mfma_f32_16x16x32_bf16 v[12:15], v[20:23], v[84:87], v[4:7]
	v_mfma_f32_16x16x32_bf16 v[4:7], v[24:27], v[60:63], 0
	v_mfma_f32_16x16x32_bf16 v[172:175], v[28:31], v[84:87], v[4:7]
	v_mfma_f32_16x16x32_bf16 v[4:7], v[16:19], v[98:101], 0
	v_mfma_f32_16x16x32_bf16 v[180:183], v[20:23], v[102:105], v[4:7]
	v_mfma_f32_16x16x32_bf16 v[4:7], v[24:27], v[98:101], 0
	v_mfma_f32_16x16x32_bf16 v[184:187], v[28:31], v[102:105], v[4:7]
	v_mfma_f32_16x16x32_bf16 v[4:7], v[16:19], v[114:117], 0
	v_mfma_f32_16x16x32_bf16 v[188:191], v[20:23], v[118:121], v[4:7]
	v_mfma_f32_16x16x32_bf16 v[4:7], v[24:27], v[114:117], 0
	v_mfma_f32_16x16x32_bf16 v[192:195], v[28:31], v[118:121], v[4:7]
	v_mfma_f32_16x16x32_bf16 v[4:7], v[16:19], v[122:125], 0
	v_mfma_f32_16x16x32_bf16 v[196:199], v[20:23], v[126:129], v[4:7]
	v_mfma_f32_16x16x32_bf16 v[4:7], v[24:27], v[122:125], 0
	v_mfma_f32_16x16x32_bf16 v[200:203], v[28:31], v[126:129], v[4:7]
	s_setprio 0
	s_barrier
	s_add_i32 s31, 0, 0x18000
	s_add_i32 s13, 0, 0x1c000
	v_add_u32_e32 v132, s31, v97
	v_add_u32_e32 v133, s13, v97
	s_nop 0
	ds_read_b128 v[4:7], v132
	ds_read_b128 v[24:27], v132 offset:1024
	ds_read_b128 v[28:31], v132 offset:2048
	ds_read_b128 v[60:63], v132 offset:3072
	ds_read_b128 v[204:207], v133
	ds_read_b128 v[208:211], v133 offset:1024
	ds_read_b128 v[212:215], v133 offset:2048
	ds_read_b128 v[216:219], v133 offset:3072
	s_add_u32 s2, s42, 0x804000
	s_addc_u32 s3, s43, 0
	s_mov_b32 m0, s39
	v_lshl_add_u64 v[84:85], s[2:3], 0, v[134:135]
	ds_read_b128 v[16:19], v151 offset:32768
	ds_read_b128 v[20:23], v151 offset:33792
	ds_read_b128 v[220:223], v151 offset:34816
	ds_read_b128 v[224:227], v151 offset:35840
	ds_read_b128 v[228:231], v151 offset:36864
	ds_read_b128 v[234:237], v151 offset:37888
	ds_read_b128 v[238:241], v151 offset:38912
	ds_read_b128 v[242:245], v151 offset:39936
	global_load_lds_dwordx4 v[84:85], off
	v_lshl_add_u64 v[84:85], s[2:3], 0, v[138:139]
	s_mov_b32 m0, s56
	s_nop 0
	global_load_lds_dwordx4 v[84:85], off
	s_sleep 2
	s_waitcnt vmcnt(8)
	s_waitcnt lgkmcnt(0)
	s_barrier
	s_setprio 1
	s_waitcnt lgkmcnt(0)
	v_mfma_f32_16x16x32_bf16 v[64:67], v[4:7], v[16:19], v[64:67]
	v_mfma_f32_16x16x32_bf16 v[118:121], v[24:27], v[20:23], v[64:67]
	v_mfma_f32_16x16x32_bf16 v[64:67], v[28:31], v[16:19], v[68:71]
	v_mfma_f32_16x16x32_bf16 v[114:117], v[60:63], v[20:23], v[64:67]
	v_mfma_f32_16x16x32_bf16 v[64:67], v[4:7], v[220:223], v[72:75]
	v_mfma_f32_16x16x32_bf16 v[102:105], v[24:27], v[224:227], v[64:67]
	v_mfma_f32_16x16x32_bf16 v[64:67], v[28:31], v[220:223], v[76:79]
	v_mfma_f32_16x16x32_bf16 v[98:101], v[60:63], v[224:227], v[64:67]
	v_mfma_f32_16x16x32_bf16 v[64:67], v[4:7], v[228:231], v[80:83]
	v_mfma_f32_16x16x32_bf16 v[84:87], v[24:27], v[234:237], v[64:67]
	v_mfma_f32_16x16x32_bf16 v[64:67], v[28:31], v[228:231], v[88:91]
	v_mfma_f32_16x16x32_bf16 v[80:83], v[60:63], v[234:237], v[64:67]
	v_mfma_f32_16x16x32_bf16 v[64:67], v[4:7], v[238:241], v[92:95]
	v_mfma_f32_16x16x32_bf16 v[68:71], v[24:27], v[242:245], v[64:67]
	v_mfma_f32_16x16x32_bf16 v[64:67], v[28:31], v[238:241], v[106:109]
	v_mfma_f32_16x16x32_bf16 v[64:67], v[60:63], v[242:245], v[64:67]
	s_setprio 0
	s_setprio 1
	v_mfma_f32_16x16x32_bf16 v[72:75], v[204:207], v[16:19], v[110:113]
	v_mfma_f32_16x16x32_bf16 v[16:19], v[212:215], v[16:19], v[32:35]
	v_mfma_f32_16x16x32_bf16 v[122:125], v[216:219], v[20:23], v[16:19]
	v_mfma_f32_16x16x32_bf16 v[16:19], v[204:207], v[220:223], v[36:39]
	v_mfma_f32_16x16x32_bf16 v[110:113], v[208:211], v[224:227], v[16:19]
	v_mfma_f32_16x16x32_bf16 v[16:19], v[212:215], v[220:223], v[40:43]
	v_mfma_f32_16x16x32_bf16 v[106:109], v[216:219], v[224:227], v[16:19]
	v_mfma_f32_16x16x32_bf16 v[16:19], v[204:207], v[228:231], v[44:47]
	v_mfma_f32_16x16x32_bf16 v[92:95], v[208:211], v[234:237], v[16:19]
	v_mfma_f32_16x16x32_bf16 v[16:19], v[212:215], v[228:231], v[48:51]
	v_mfma_f32_16x16x32_bf16 v[88:91], v[216:219], v[234:237], v[16:19]
	v_mfma_f32_16x16x32_bf16 v[16:19], v[204:207], v[238:241], v[52:55]
	v_mfma_f32_16x16x32_bf16 v[76:79], v[208:211], v[242:245], v[16:19]
	v_mfma_f32_16x16x32_bf16 v[16:19], v[212:215], v[238:241], v[56:59]
	v_mfma_f32_16x16x32_bf16 v[126:129], v[208:211], v[20:23], v[72:75]
	v_mfma_f32_16x16x32_bf16 v[72:75], v[216:219], v[242:245], v[16:19]
	s_setprio 0
	s_barrier
; template <class Epi, class Sched, bool ALIGN_EPI = false, bool SP2 = false>
; __device__ __forceinline__ void gemm_phase(PG8_LAS unsigned char* lds, const Gemm g, const Sched& S, const Epi& E) {
;     ...
;         for (int t = (Epi::PEEL ? 2 : 0); t < nt; t += 2) {
;             const bool last = (t == nt - 2);
;             const char* a1 = cA + (size_t)(t + 1) * kstepA;
;             const char* a2 = last ? nA : cA + (size_t)(t + 2) * kstepA; const char* b2 = last ? nB : cB + (size_t)(t + 2) * kstepB;
;             const char* a3 = a2 + kstepA; const char* b3 = b2 + kstepB;
	s_mov_b64 s[2:3], 0x180
	s_add_i32 s31, s31, s10
	s_nop 1
	v_lshl_add_u64 v[16:17], v[176:177], 0, s[2:3]
	s_mov_b32 m0, s31
	s_add_i32 s12, s31, 0x2000
	ds_read_b128 v[40:43], v151 offset:49152
	ds_read_b128 v[44:47], v151 offset:50176
	ds_read_b128 v[220:223], v151 offset:51200
	ds_read_b128 v[224:227], v151 offset:52224
	ds_read_b128 v[228:231], v151 offset:53248
	ds_read_b128 v[234:237], v151 offset:54272
	ds_read_b128 v[238:241], v151 offset:55296
	ds_read_b128 v[242:245], v151 offset:56320
	global_load_lds_dwordx4 v[16:17], off
	v_lshl_add_u64 v[16:17], v[178:179], 0, s[2:3]
	s_add_u32 s2, s24, 0x40180
	s_mov_b32 m0, s12
	s_addc_u32 s3, s25, 0
	s_add_i32 s13, s13, s10
	global_load_lds_dwordx4 v[16:17], off
	v_lshl_add_u64 v[16:17], s[2:3], 0, v[136:137]
	s_mov_b32 m0, s13
	s_add_i32 s11, s13, 0x2000
	global_load_lds_dwordx4 v[16:17], off
	v_lshl_add_u64 v[16:17], s[2:3], 0, v[140:141]
	s_mov_b32 m0, s11
	s_nop 0
	global_load_lds_dwordx4 v[16:17], off
	v_lshl_add_u64 v[16:17], s[44:45], 0, v[134:135]
	s_mov_b32 m0, s59
	s_nop 0
	global_load_lds_dwordx4 v[16:17], off
	v_lshl_add_u64 v[16:17], s[44:45], 0, v[138:139]
	s_mov_b32 m0, s96
	s_nop 0
	global_load_lds_dwordx4 v[16:17], off
	s_sleep 2
	s_waitcnt vmcnt(8)
	s_waitcnt lgkmcnt(0)
	s_barrier
	s_setprio 1
	s_waitcnt lgkmcnt(0)
	v_mfma_f32_16x16x32_bf16 v[16:19], v[4:7], v[40:43], v[146:149]
	v_mfma_f32_16x16x32_bf16 v[52:55], v[24:27], v[44:47], v[16:19]
	v_mfma_f32_16x16x32_bf16 v[16:19], v[28:31], v[40:43], v[152:155]
	v_mfma_f32_16x16x32_bf16 v[48:51], v[60:63], v[44:47], v[16:19]
	v_mfma_f32_16x16x32_bf16 v[16:19], v[4:7], v[220:223], v[156:159]
	v_mfma_f32_16x16x32_bf16 v[36:39], v[24:27], v[224:227], v[16:19]
	v_mfma_f32_16x16x32_bf16 v[16:19], v[28:31], v[220:223], v[160:163]
	v_mfma_f32_16x16x32_bf16 v[32:35], v[60:63], v[224:227], v[16:19]
	v_mfma_f32_16x16x32_bf16 v[16:19], v[4:7], v[228:231], v[164:167]
	v_mfma_f32_16x16x32_bf16 v[0:3], v[4:7], v[238:241], v[0:3]
	v_mfma_f32_16x16x32_bf16 v[20:23], v[24:27], v[234:237], v[16:19]
	v_mfma_f32_16x16x32_bf16 v[16:19], v[28:31], v[228:231], v[168:171]
	v_mfma_f32_16x16x32_bf16 v[4:7], v[24:27], v[242:245], v[0:3]
	v_mfma_f32_16x16x32_bf16 v[0:3], v[28:31], v[238:241], v[8:11]
	v_mfma_f32_16x16x32_bf16 v[16:19], v[60:63], v[234:237], v[16:19]
	v_mfma_f32_16x16x32_bf16 v[0:3], v[60:63], v[242:245], v[0:3]
	s_setprio 0
	s_setprio 1
	v_mfma_f32_16x16x32_bf16 v[8:11], v[204:207], v[40:43], v[12:15]
	v_mfma_f32_16x16x32_bf16 v[60:63], v[208:211], v[44:47], v[8:11]
	v_mfma_f32_16x16x32_bf16 v[8:11], v[212:215], v[40:43], v[172:175]
	v_mfma_f32_16x16x32_bf16 v[56:59], v[216:219], v[44:47], v[8:11]
	v_mfma_f32_16x16x32_bf16 v[8:11], v[204:207], v[220:223], v[180:183]
	v_mfma_f32_16x16x32_bf16 v[44:47], v[208:211], v[224:227], v[8:11]
	v_mfma_f32_16x16x32_bf16 v[8:11], v[212:215], v[220:223], v[184:187]
	v_mfma_f32_16x16x32_bf16 v[40:43], v[216:219], v[224:227], v[8:11]
	v_mfma_f32_16x16x32_bf16 v[8:11], v[204:207], v[228:231], v[188:191]
	v_mfma_f32_16x16x32_bf16 v[28:31], v[208:211], v[234:237], v[8:11]
	v_mfma_f32_16x16x32_bf16 v[8:11], v[212:215], v[228:231], v[192:195]
	v_mfma_f32_16x16x32_bf16 v[24:27], v[216:219], v[234:237], v[8:11]
	v_mfma_f32_16x16x32_bf16 v[8:11], v[204:207], v[238:241], v[196:199]
	v_mfma_f32_16x16x32_bf16 v[12:15], v[208:211], v[242:245], v[8:11]
	v_mfma_f32_16x16x32_bf16 v[8:11], v[212:215], v[238:241], v[200:203]
	v_mfma_f32_16x16x32_bf16 v[8:11], v[216:219], v[242:245], v[8:11]
	s_setprio 0
	s_barrier
	s_add_u32 s3, s24, 0x200
	s_addc_u32 s2, s25, 0
	s_add_u32 s24, s42, 0xc04000
	s_addc_u32 s25, s43, 0
	s_mov_b32 s18, 0
.LBB0_250:
	ds_read_b128 v[146:149], v130
	ds_read_b128 v[152:155], v130 offset:1024
	ds_read_b128 v[156:159], v130 offset:2048
	ds_read_b128 v[160:163], v130 offset:3072
	ds_read_b128 v[164:167], v131
	ds_read_b128 v[168:171], v131 offset:1024
	ds_read_b128 v[172:175], v131 offset:2048
	ds_read_b128 v[180:183], v131 offset:3072
	s_add_u32 s16, s24, 0x3fc000
	s_addc_u32 s17, s25, 0
	s_cmp_eq_u32 s18, 12
	s_cselect_b32 s28, s47, s16
	s_cselect_b32 s29, s27, s17
	s_cselect_b32 s44, s54, s3
	s_cselect_b32 s45, s49, s2
	s_add_u32 s42, s28, 0x400000
	s_addc_u32 s43, s29, 0
	s_mov_b32 m0, s55
	v_lshl_add_u64 v[176:177], s[24:25], 0, v[144:145]
	ds_read_b128 v[184:187], v151
	ds_read_b128 v[188:191], v151 offset:1024
	ds_read_b128 v[192:195], v151 offset:2048
	ds_read_b128 v[196:199], v151 offset:3072
	ds_read_b128 v[200:203], v151 offset:4096
	ds_read_b128 v[204:207], v151 offset:5120
	ds_read_b128 v[208:211], v151 offset:6144
	ds_read_b128 v[212:215], v151 offset:7168
	global_load_lds_dwordx4 v[176:177], off
	v_lshl_add_u64 v[176:177], s[24:25], 0, v[142:143]
	s_mov_b32 m0, s98
	s_nop 0
	global_load_lds_dwordx4 v[176:177], off
	s_sleep 2
	s_waitcnt vmcnt(8)
	s_waitcnt lgkmcnt(0)
	s_barrier
	s_setprio 1
	s_waitcnt lgkmcnt(0)
	v_mfma_f32_16x16x32_bf16 v[118:121], v[146:149], v[184:187], v[118:121]
	v_mfma_f32_16x16x32_bf16 v[114:117], v[156:159], v[184:187], v[114:117]
	v_mfma_f32_16x16x32_bf16 v[102:105], v[146:149], v[192:195], v[102:105]
	v_mfma_f32_16x16x32_bf16 v[98:101], v[156:159], v[192:195], v[98:101]
	v_mfma_f32_16x16x32_bf16 v[84:87], v[146:149], v[200:203], v[84:87]
	v_mfma_f32_16x16x32_bf16 v[80:83], v[156:159], v[200:203], v[80:83]
	v_mfma_f32_16x16x32_bf16 v[68:71], v[146:149], v[208:211], v[68:71]
	v_mfma_f32_16x16x32_bf16 v[64:67], v[156:159], v[208:211], v[64:67]
	v_mfma_f32_16x16x32_bf16 v[118:121], v[152:155], v[188:191], v[118:121]
	v_mfma_f32_16x16x32_bf16 v[114:117], v[160:163], v[188:191], v[114:117]
	v_mfma_f32_16x16x32_bf16 v[102:105], v[152:155], v[196:199], v[102:105]
	v_mfma_f32_16x16x32_bf16 v[98:101], v[160:163], v[196:199], v[98:101]
	v_mfma_f32_16x16x32_bf16 v[84:87], v[152:155], v[204:207], v[84:87]
	v_mfma_f32_16x16x32_bf16 v[80:83], v[160:163], v[204:207], v[80:83]
	v_mfma_f32_16x16x32_bf16 v[68:71], v[152:155], v[212:215], v[68:71]
	v_mfma_f32_16x16x32_bf16 v[64:67], v[160:163], v[212:215], v[64:67]
	s_setprio 0
	s_setprio 1
	v_mfma_f32_16x16x32_bf16 v[126:129], v[164:167], v[184:187], v[126:129]
	v_mfma_f32_16x16x32_bf16 v[122:125], v[172:175], v[184:187], v[122:125]
	v_mfma_f32_16x16x32_bf16 v[110:113], v[164:167], v[192:195], v[110:113]
	v_mfma_f32_16x16x32_bf16 v[106:109], v[172:175], v[192:195], v[106:109]
	v_mfma_f32_16x16x32_bf16 v[92:95], v[164:167], v[200:203], v[92:95]
	v_mfma_f32_16x16x32_bf16 v[88:91], v[172:175], v[200:203], v[88:91]
	v_mfma_f32_16x16x32_bf16 v[76:79], v[164:167], v[208:211], v[76:79]
	v_mfma_f32_16x16x32_bf16 v[72:75], v[172:175], v[208:211], v[72:75]
	v_mfma_f32_16x16x32_bf16 v[126:129], v[168:171], v[188:191], v[126:129]
	v_mfma_f32_16x16x32_bf16 v[122:125], v[180:183], v[188:191], v[122:125]
	v_mfma_f32_16x16x32_bf16 v[110:113], v[168:171], v[196:199], v[110:113]
	v_mfma_f32_16x16x32_bf16 v[106:109], v[180:183], v[196:199], v[106:109]
	v_mfma_f32_16x16x32_bf16 v[92:95], v[168:171], v[204:207], v[92:95]
	v_mfma_f32_16x16x32_bf16 v[88:91], v[180:183], v[204:207], v[88:91]
	v_mfma_f32_16x16x32_bf16 v[76:79], v[168:171], v[212:215], v[76:79]
	v_mfma_f32_16x16x32_bf16 v[72:75], v[180:183], v[212:215], v[72:75]
	s_setprio 0
	s_barrier
	s_mov_b32 m0, s99
	v_lshl_add_u64 v[176:177], s[44:45], 0, v[136:137]
	s_add_u32 s16, s44, 0x40000
	ds_read_b128 v[184:187], v151 offset:16384
	ds_read_b128 v[188:191], v151 offset:17408
	ds_read_b128 v[192:195], v151 offset:18432
	ds_read_b128 v[196:199], v151 offset:19456
	ds_read_b128 v[200:203], v151 offset:20480
	ds_read_b128 v[204:207], v151 offset:21504
	ds_read_b128 v[208:211], v151 offset:22528
	ds_read_b128 v[212:215], v151 offset:23552
	global_load_lds_dwordx4 v[176:177], off
	v_lshl_add_u64 v[178:179], s[44:45], 0, v[140:141]
	s_mov_b32 m0, vcc_lo
	s_addc_u32 s17, s45, 0
	global_load_lds_dwordx4 v[178:179], off
	v_lshl_add_u64 v[216:217], s[16:17], 0, v[136:137]
	s_mov_b32 m0, vcc_hi
	s_nop 0
	global_load_lds_dwordx4 v[216:217], off
	v_lshl_add_u64 v[216:217], s[16:17], 0, v[140:141]
	s_mov_b32 m0, s30
	s_nop 0
	global_load_lds_dwordx4 v[216:217], off
	v_lshl_add_u64 v[216:217], s[28:29], 0, v[134:135]
	s_mov_b32 m0, s22
	s_nop 0
	global_load_lds_dwordx4 v[216:217], off
	v_lshl_add_u64 v[216:217], s[28:29], 0, v[138:139]
	s_mov_b32 m0, s23
	s_nop 0
	global_load_lds_dwordx4 v[216:217], off
	s_sleep 2
	s_waitcnt vmcnt(8)
	s_waitcnt lgkmcnt(0)
	s_barrier
	s_setprio 1
	s_waitcnt lgkmcnt(0)
	v_mfma_f32_16x16x32_bf16 v[52:55], v[146:149], v[184:187], v[52:55]
	v_mfma_f32_16x16x32_bf16 v[48:51], v[156:159], v[184:187], v[48:51]
	v_mfma_f32_16x16x32_bf16 v[36:39], v[146:149], v[192:195], v[36:39]
	v_mfma_f32_16x16x32_bf16 v[32:35], v[156:159], v[192:195], v[32:35]
	v_mfma_f32_16x16x32_bf16 v[20:23], v[146:149], v[200:203], v[20:23]
	v_mfma_f32_16x16x32_bf16 v[16:19], v[156:159], v[200:203], v[16:19]
	v_mfma_f32_16x16x32_bf16 v[4:7], v[146:149], v[208:211], v[4:7]
	v_mfma_f32_16x16x32_bf16 v[0:3], v[156:159], v[208:211], v[0:3]
	v_mfma_f32_16x16x32_bf16 v[52:55], v[152:155], v[188:191], v[52:55]
	v_mfma_f32_16x16x32_bf16 v[48:51], v[160:163], v[188:191], v[48:51]
	v_mfma_f32_16x16x32_bf16 v[36:39], v[152:155], v[196:199], v[36:39]
	v_mfma_f32_16x16x32_bf16 v[32:35], v[160:163], v[196:199], v[32:35]
	v_mfma_f32_16x16x32_bf16 v[20:23], v[152:155], v[204:207], v[20:23]
	v_mfma_f32_16x16x32_bf16 v[16:19], v[160:163], v[204:207], v[16:19]
	v_mfma_f32_16x16x32_bf16 v[4:7], v[152:155], v[212:215], v[4:7]
	v_mfma_f32_16x16x32_bf16 v[0:3], v[160:163], v[212:215], v[0:3]
	s_setprio 0
	s_setprio 1
	v_mfma_f32_16x16x32_bf16 v[60:63], v[164:167], v[184:187], v[60:63]
	v_mfma_f32_16x16x32_bf16 v[56:59], v[172:175], v[184:187], v[56:59]
	v_mfma_f32_16x16x32_bf16 v[44:47], v[164:167], v[192:195], v[44:47]
	v_mfma_f32_16x16x32_bf16 v[40:43], v[172:175], v[192:195], v[40:43]
	v_mfma_f32_16x16x32_bf16 v[28:31], v[164:167], v[200:203], v[28:31]
	v_mfma_f32_16x16x32_bf16 v[24:27], v[172:175], v[200:203], v[24:27]
	v_mfma_f32_16x16x32_bf16 v[12:15], v[164:167], v[208:211], v[12:15]
	v_mfma_f32_16x16x32_bf16 v[8:11], v[172:175], v[208:211], v[8:11]
	v_mfma_f32_16x16x32_bf16 v[60:63], v[168:171], v[188:191], v[60:63]
	v_mfma_f32_16x16x32_bf16 v[56:59], v[180:183], v[188:191], v[56:59]
	v_mfma_f32_16x16x32_bf16 v[44:47], v[168:171], v[196:199], v[44:47]
	v_mfma_f32_16x16x32_bf16 v[40:43], v[180:183], v[196:199], v[40:43]
	v_mfma_f32_16x16x32_bf16 v[28:31], v[168:171], v[204:207], v[28:31]
	v_mfma_f32_16x16x32_bf16 v[24:27], v[180:183], v[204:207], v[24:27]
	v_mfma_f32_16x16x32_bf16 v[12:15], v[168:171], v[212:215], v[12:15]
	v_mfma_f32_16x16x32_bf16 v[8:11], v[180:183], v[212:215], v[8:11]
	s_setprio 0
	s_barrier
	ds_read_b128 v[146:149], v132
	ds_read_b128 v[152:155], v132 offset:1024
	ds_read_b128 v[156:159], v132 offset:2048
	ds_read_b128 v[160:163], v132 offset:3072
	ds_read_b128 v[164:167], v133
	ds_read_b128 v[168:171], v133 offset:1024
	ds_read_b128 v[172:175], v133 offset:2048
	ds_read_b128 v[180:183], v133 offset:3072
	s_add_u32 s16, s28, 0x4000
	s_addc_u32 s17, s29, 0
	s_mov_b32 m0, s39
	v_lshl_add_u64 v[216:217], s[16:17], 0, v[134:135]
	ds_read_b128 v[184:187], v151 offset:32768
	ds_read_b128 v[188:191], v151 offset:33792
	ds_read_b128 v[192:195], v151 offset:34816
	ds_read_b128 v[196:199], v151 offset:35840
	ds_read_b128 v[200:203], v151 offset:36864
	ds_read_b128 v[204:207], v151 offset:37888
	ds_read_b128 v[208:211], v151 offset:38912
	ds_read_b128 v[212:215], v151 offset:39936
	global_load_lds_dwordx4 v[216:217], off
	v_lshl_add_u64 v[216:217], s[16:17], 0, v[138:139]
	s_mov_b32 m0, s56
	s_nop 0
	global_load_lds_dwordx4 v[216:217], off
	s_sleep 2
	s_waitcnt vmcnt(8)
	s_waitcnt lgkmcnt(0)
	s_barrier
	s_setprio 1
	s_waitcnt lgkmcnt(0)
	v_mfma_f32_16x16x32_bf16 v[118:121], v[146:149], v[184:187], v[118:121]
	v_mfma_f32_16x16x32_bf16 v[114:117], v[156:159], v[184:187], v[114:117]
	v_mfma_f32_16x16x32_bf16 v[102:105], v[146:149], v[192:195], v[102:105]
	v_mfma_f32_16x16x32_bf16 v[98:101], v[156:159], v[192:195], v[98:101]
	v_mfma_f32_16x16x32_bf16 v[84:87], v[146:149], v[200:203], v[84:87]
	v_mfma_f32_16x16x32_bf16 v[80:83], v[156:159], v[200:203], v[80:83]
	v_mfma_f32_16x16x32_bf16 v[68:71], v[146:149], v[208:211], v[68:71]
	v_mfma_f32_16x16x32_bf16 v[64:67], v[156:159], v[208:211], v[64:67]
	v_mfma_f32_16x16x32_bf16 v[118:121], v[152:155], v[188:191], v[118:121]
	v_mfma_f32_16x16x32_bf16 v[114:117], v[160:163], v[188:191], v[114:117]
	v_mfma_f32_16x16x32_bf16 v[102:105], v[152:155], v[196:199], v[102:105]
	v_mfma_f32_16x16x32_bf16 v[98:101], v[160:163], v[196:199], v[98:101]
	v_mfma_f32_16x16x32_bf16 v[84:87], v[152:155], v[204:207], v[84:87]
	v_mfma_f32_16x16x32_bf16 v[80:83], v[160:163], v[204:207], v[80:83]
	v_mfma_f32_16x16x32_bf16 v[68:71], v[152:155], v[212:215], v[68:71]
	v_mfma_f32_16x16x32_bf16 v[64:67], v[160:163], v[212:215], v[64:67]
	s_setprio 0
	s_setprio 1
	v_mfma_f32_16x16x32_bf16 v[126:129], v[164:167], v[184:187], v[126:129]
	v_mfma_f32_16x16x32_bf16 v[122:125], v[172:175], v[184:187], v[122:125]
	v_mfma_f32_16x16x32_bf16 v[110:113], v[164:167], v[192:195], v[110:113]
	v_mfma_f32_16x16x32_bf16 v[106:109], v[172:175], v[192:195], v[106:109]
	v_mfma_f32_16x16x32_bf16 v[92:95], v[164:167], v[200:203], v[92:95]
	v_mfma_f32_16x16x32_bf16 v[88:91], v[172:175], v[200:203], v[88:91]
	v_mfma_f32_16x16x32_bf16 v[76:79], v[164:167], v[208:211], v[76:79]
	v_mfma_f32_16x16x32_bf16 v[72:75], v[172:175], v[208:211], v[72:75]
	v_mfma_f32_16x16x32_bf16 v[126:129], v[168:171], v[188:191], v[126:129]
	v_mfma_f32_16x16x32_bf16 v[122:125], v[180:183], v[188:191], v[122:125]
	v_mfma_f32_16x16x32_bf16 v[110:113], v[168:171], v[196:199], v[110:113]
	v_mfma_f32_16x16x32_bf16 v[106:109], v[180:183], v[196:199], v[106:109]
	v_mfma_f32_16x16x32_bf16 v[92:95], v[168:171], v[204:207], v[92:95]
	v_mfma_f32_16x16x32_bf16 v[88:91], v[180:183], v[204:207], v[88:91]
	v_mfma_f32_16x16x32_bf16 v[76:79], v[168:171], v[212:215], v[76:79]
	v_mfma_f32_16x16x32_bf16 v[72:75], v[180:183], v[212:215], v[72:75]
	s_setprio 0
	s_barrier
; #define PG8_BAR __builtin_amdgcn_s_barrier()
; template <class Epi, class Sched, bool ALIGN_EPI = false, bool SP2 = false>
; __device__ __forceinline__ void gemm_phase(PG8_LAS unsigned char* lds, const Gemm g, const Sched& S, const Epi& E) {
;     ...
;             PG8_ITER(8);
;         }
;     ...
;         if constexpr (ALIGN_EPI) { if (wr == 0) PG8_BAR; }
	s_mov_b32 m0, s31
	v_lshl_add_u64 v[176:177], v[176:177], 0, s[36:37]
	s_add_u32 s16, s44, 0x40080
	ds_read_b128 v[184:187], v151 offset:49152
	ds_read_b128 v[188:191], v151 offset:50176
	ds_read_b128 v[192:195], v151 offset:51200
	ds_read_b128 v[196:199], v151 offset:52224
	ds_read_b128 v[200:203], v151 offset:53248
	ds_read_b128 v[204:207], v151 offset:54272
	ds_read_b128 v[208:211], v151 offset:55296
	ds_read_b128 v[212:215], v151 offset:56320
	global_load_lds_dwordx4 v[176:177], off
	v_lshl_add_u64 v[176:177], v[178:179], 0, s[36:37]
	s_mov_b32 m0, s12
	s_addc_u32 s17, s45, 0
	global_load_lds_dwordx4 v[176:177], off
	v_lshl_add_u64 v[176:177], s[16:17], 0, v[136:137]
	s_mov_b32 m0, s13
	s_nop 0
	global_load_lds_dwordx4 v[176:177], off
	v_lshl_add_u64 v[176:177], s[16:17], 0, v[140:141]
	s_mov_b32 m0, s11
	s_nop 0
	global_load_lds_dwordx4 v[176:177], off
	v_lshl_add_u64 v[176:177], s[42:43], 0, v[134:135]
	s_mov_b32 m0, s59
	s_nop 0
	global_load_lds_dwordx4 v[176:177], off
	v_lshl_add_u64 v[176:177], s[42:43], 0, v[138:139]
	s_mov_b32 m0, s96
	s_nop 0
	global_load_lds_dwordx4 v[176:177], off
	s_sleep 2
	s_waitcnt vmcnt(8)
	s_waitcnt lgkmcnt(0)
	s_barrier
	s_setprio 1
	s_waitcnt lgkmcnt(0)
	v_mfma_f32_16x16x32_bf16 v[52:55], v[146:149], v[184:187], v[52:55]
	v_mfma_f32_16x16x32_bf16 v[48:51], v[156:159], v[184:187], v[48:51]
	v_mfma_f32_16x16x32_bf16 v[36:39], v[146:149], v[192:195], v[36:39]
	v_mfma_f32_16x16x32_bf16 v[32:35], v[156:159], v[192:195], v[32:35]
	v_mfma_f32_16x16x32_bf16 v[20:23], v[146:149], v[200:203], v[20:23]
	v_mfma_f32_16x16x32_bf16 v[16:19], v[156:159], v[200:203], v[16:19]
	v_mfma_f32_16x16x32_bf16 v[4:7], v[146:149], v[208:211], v[4:7]
	v_mfma_f32_16x16x32_bf16 v[0:3], v[156:159], v[208:211], v[0:3]
	v_mfma_f32_16x16x32_bf16 v[52:55], v[152:155], v[188:191], v[52:55]
	v_mfma_f32_16x16x32_bf16 v[48:51], v[160:163], v[188:191], v[48:51]
	v_mfma_f32_16x16x32_bf16 v[36:39], v[152:155], v[196:199], v[36:39]
	v_mfma_f32_16x16x32_bf16 v[32:35], v[160:163], v[196:199], v[32:35]
	v_mfma_f32_16x16x32_bf16 v[20:23], v[152:155], v[204:207], v[20:23]
	v_mfma_f32_16x16x32_bf16 v[16:19], v[160:163], v[204:207], v[16:19]
	v_mfma_f32_16x16x32_bf16 v[4:7], v[152:155], v[212:215], v[4:7]
	v_mfma_f32_16x16x32_bf16 v[0:3], v[160:163], v[212:215], v[0:3]
	s_setprio 0
	s_setprio 1
	v_mfma_f32_16x16x32_bf16 v[60:63], v[164:167], v[184:187], v[60:63]
	v_mfma_f32_16x16x32_bf16 v[56:59], v[172:175], v[184:187], v[56:59]
	v_mfma_f32_16x16x32_bf16 v[44:47], v[164:167], v[192:195], v[44:47]
	v_mfma_f32_16x16x32_bf16 v[40:43], v[172:175], v[192:195], v[40:43]
	v_mfma_f32_16x16x32_bf16 v[28:31], v[164:167], v[200:203], v[28:31]
	v_mfma_f32_16x16x32_bf16 v[24:27], v[172:175], v[200:203], v[24:27]
	v_mfma_f32_16x16x32_bf16 v[12:15], v[164:167], v[208:211], v[12:15]
	v_mfma_f32_16x16x32_bf16 v[8:11], v[172:175], v[208:211], v[8:11]
	v_mfma_f32_16x16x32_bf16 v[60:63], v[168:171], v[188:191], v[60:63]
	v_mfma_f32_16x16x32_bf16 v[56:59], v[180:183], v[188:191], v[56:59]
	v_mfma_f32_16x16x32_bf16 v[44:47], v[168:171], v[196:199], v[44:47]
	v_mfma_f32_16x16x32_bf16 v[40:43], v[180:183], v[196:199], v[40:43]
	v_mfma_f32_16x16x32_bf16 v[28:31], v[168:171], v[204:207], v[28:31]
	v_mfma_f32_16x16x32_bf16 v[24:27], v[180:183], v[204:207], v[24:27]
	v_mfma_f32_16x16x32_bf16 v[12:15], v[168:171], v[212:215], v[12:15]
	v_mfma_f32_16x16x32_bf16 v[8:11], v[180:183], v[212:215], v[8:11]
	s_setprio 0
	s_barrier
	s_add_i32 s18, s18, 2
	s_add_u32 s3, s3, 0x100
	s_addc_u32 s2, s2, 0
	s_add_u32 s24, s24, 0x800000
	s_addc_u32 s25, s25, 0
	s_cmp_gt_u32 s18, 13
	s_cbranch_scc0 .LBB0_250
	v_readlane_b32 s2, v255, 33
	v_readlane_b32 s3, v255, 34
	v_readlane_b32 s12, v255, 31
	s_and_b64 vcc, exec, s[2:3]
	v_readlane_b32 s13, v255, 32
	s_cbranch_vccz .LBB0_253
	s_barrier

; template <class Epi, class Sched, bool ALIGN_EPI = false, bool SP2 = false>
; __device__ __forceinline__ void gemm_phase(PG8_LAS unsigned char* lds, const Gemm g, const Sched& S, const Epi& E) {
;     ...
;         for (int t = (Epi::PEEL ? 2 : 0); t < nt; t += 2) {
;             const bool last = (t == nt - 2);
;             const char* a1 = cA + (size_t)(t + 1) * kstepA;
;             const char* a2 = last ? nA : cA + (size_t)(t + 2) * kstepA; const char* b2 = last ? nB : cB + (size_t)(t + 2) * kstepB;
;             const char* a3 = a2 + kstepA; const char* b3 = b2 + kstepB;
.LBB0_345:
	s_add_i32 s10, s10, 2
	s_add_u32 s44, s42, s34
	s_addc_u32 s45, s43, s35
	s_add_i32 s18, 0, 0x10000
	s_and_b64 s[2:3], exec, s[46:47]
	s_cselect_b32 s3, s13, s59
	s_cselect_b32 s2, s12, s58
	s_add_i32 s38, 0, 0x14000
	v_add_u32_e32 v142, s18, v97
	v_add_u32_e32 v170, s38, v97
	ds_read_b128 v[122:125], v142
	ds_read_b128 v[126:129], v142 offset:1024
	ds_read_b128 v[138:141], v142 offset:2048
	ds_read_b128 v[142:145], v142 offset:3072
	ds_read_b128 v[146:149], v170
	ds_read_b128 v[150:153], v170 offset:1024
	ds_read_b128 v[154:157], v170 offset:2048
	ds_read_b128 v[170:173], v170 offset:3072
	v_lshl_add_u64 v[178:179], s[24:25], 0, v[168:169]
	s_add_i32 m0, s97, 0xc000
	ds_read_b128 v[174:177], v188
	ds_read_b128 v[180:183], v188 offset:1024
	ds_read_b128 v[184:187], v188 offset:2048
	ds_read_b128 v[190:193], v188 offset:3072
	ds_read_b128 v[194:197], v188 offset:4096
	ds_read_b128 v[198:201], v188 offset:5120
	ds_read_b128 v[202:205], v188 offset:6144
	ds_read_b128 v[206:209], v188 offset:7168
	global_load_lds_dwordx4 v[178:179], off
	v_lshl_add_u64 v[178:179], s[24:25], 0, v[166:167]
	s_add_i32 m0, s97, 0xe000
	s_nop 0
	global_load_lds_dwordx4 v[178:179], off
	s_sleep 2
	s_waitcnt vmcnt(8)
	s_waitcnt lgkmcnt(0)
	s_barrier
	s_setprio 1
	s_waitcnt lgkmcnt(0)
	v_mfma_f32_16x16x32_bf16 v[134:137], v[122:125], v[174:177], v[134:137]
	v_mfma_f32_16x16x32_bf16 v[130:133], v[138:141], v[174:177], v[130:133]
	v_mfma_f32_16x16x32_bf16 v[110:113], v[122:125], v[184:187], v[110:113]
	v_mfma_f32_16x16x32_bf16 v[106:109], v[138:141], v[184:187], v[106:109]
	v_mfma_f32_16x16x32_bf16 v[92:95], v[122:125], v[194:197], v[92:95]
	v_mfma_f32_16x16x32_bf16 v[88:91], v[138:141], v[194:197], v[88:91]
	v_mfma_f32_16x16x32_bf16 v[76:79], v[122:125], v[202:205], v[76:79]
	v_mfma_f32_16x16x32_bf16 v[72:75], v[138:141], v[202:205], v[72:75]
	v_mfma_f32_16x16x32_bf16 v[134:137], v[126:129], v[180:183], v[134:137]
	v_mfma_f32_16x16x32_bf16 v[130:133], v[142:145], v[180:183], v[130:133]
	v_mfma_f32_16x16x32_bf16 v[110:113], v[126:129], v[190:193], v[110:113]
	v_mfma_f32_16x16x32_bf16 v[106:109], v[142:145], v[190:193], v[106:109]
	v_mfma_f32_16x16x32_bf16 v[92:95], v[126:129], v[198:201], v[92:95]
	v_mfma_f32_16x16x32_bf16 v[88:91], v[142:145], v[198:201], v[88:91]
	v_mfma_f32_16x16x32_bf16 v[76:79], v[126:129], v[206:209], v[76:79]
	v_mfma_f32_16x16x32_bf16 v[72:75], v[142:145], v[206:209], v[72:75]
	s_setprio 0
	s_setprio 1
	v_mfma_f32_16x16x32_bf16 v[118:121], v[146:149], v[174:177], v[118:121]
	v_mfma_f32_16x16x32_bf16 v[114:117], v[154:157], v[174:177], v[114:117]
	v_mfma_f32_16x16x32_bf16 v[102:105], v[146:149], v[184:187], v[102:105]
	v_mfma_f32_16x16x32_bf16 v[98:101], v[154:157], v[184:187], v[98:101]
	v_mfma_f32_16x16x32_bf16 v[84:87], v[146:149], v[194:197], v[84:87]
	v_mfma_f32_16x16x32_bf16 v[80:83], v[154:157], v[194:197], v[80:83]
	v_mfma_f32_16x16x32_bf16 v[68:71], v[146:149], v[202:205], v[68:71]
	v_mfma_f32_16x16x32_bf16 v[64:67], v[154:157], v[202:205], v[64:67]
	v_mfma_f32_16x16x32_bf16 v[118:121], v[150:153], v[180:183], v[118:121]
	v_mfma_f32_16x16x32_bf16 v[114:117], v[170:173], v[180:183], v[114:117]
	v_mfma_f32_16x16x32_bf16 v[102:105], v[150:153], v[190:193], v[102:105]
	v_mfma_f32_16x16x32_bf16 v[98:101], v[170:173], v[190:193], v[98:101]
	v_mfma_f32_16x16x32_bf16 v[84:87], v[150:153], v[198:201], v[84:87]
	v_mfma_f32_16x16x32_bf16 v[80:83], v[170:173], v[198:201], v[80:83]
	v_mfma_f32_16x16x32_bf16 v[68:71], v[150:153], v[206:209], v[68:71]
	v_mfma_f32_16x16x32_bf16 v[64:67], v[170:173], v[206:209], v[64:67]
	s_setprio 0
	s_barrier
	s_add_i32 s18, s18, s96
	v_lshl_add_u64 v[178:179], s[2:3], 0, v[162:163]
	s_mov_b32 m0, s18
	ds_read_b128 v[174:177], v188 offset:16384
	ds_read_b128 v[180:183], v188 offset:17408
	ds_read_b128 v[184:187], v188 offset:18432
	ds_read_b128 v[190:193], v188 offset:19456
	ds_read_b128 v[194:197], v188 offset:20480
	ds_read_b128 v[198:201], v188 offset:21504
	ds_read_b128 v[202:205], v188 offset:22528
	ds_read_b128 v[206:209], v188 offset:23552
	global_load_lds_dwordx4 v[178:179], off
	s_add_i32 m0, s18, 0x2000
	v_lshl_add_u64 v[210:211], s[2:3], 0, v[158:159]
	s_add_u32 s2, s2, s48
	s_addc_u32 s3, s3, 0
	s_add_i32 s18, s38, s96
	global_load_lds_dwordx4 v[210:211], off
	v_lshl_add_u64 v[212:213], s[2:3], 0, v[162:163]
	s_mov_b32 m0, s18
	v_lshl_add_u64 v[214:215], s[2:3], 0, v[158:159]
	global_load_lds_dwordx4 v[212:213], off
	s_add_i32 m0, s18, 0x2000
	v_lshl_add_u64 v[216:217], s[42:43], 0, v[164:165]
	global_load_lds_dwordx4 v[214:215], off
	s_mov_b32 m0, s97
	s_nop 0
	global_load_lds_dwordx4 v[216:217], off
	v_lshl_add_u64 v[216:217], s[42:43], 0, v[160:161]
	s_mov_b32 m0, s22
	s_nop 0
	global_load_lds_dwordx4 v[216:217], off
	s_sleep 2
	s_waitcnt vmcnt(8)
	s_waitcnt lgkmcnt(0)
	s_barrier
	s_setprio 1
	s_waitcnt lgkmcnt(0)
	v_mfma_f32_16x16x32_bf16 v[60:63], v[122:125], v[174:177], v[60:63]
	v_mfma_f32_16x16x32_bf16 v[56:59], v[138:141], v[174:177], v[56:59]
	v_mfma_f32_16x16x32_bf16 v[44:47], v[122:125], v[184:187], v[44:47]
	v_mfma_f32_16x16x32_bf16 v[40:43], v[138:141], v[184:187], v[40:43]
	v_mfma_f32_16x16x32_bf16 v[28:31], v[122:125], v[194:197], v[28:31]
	v_mfma_f32_16x16x32_bf16 v[24:27], v[138:141], v[194:197], v[24:27]
	v_mfma_f32_16x16x32_bf16 v[12:15], v[122:125], v[202:205], v[12:15]
	v_mfma_f32_16x16x32_bf16 v[8:11], v[138:141], v[202:205], v[8:11]
	v_mfma_f32_16x16x32_bf16 v[60:63], v[126:129], v[180:183], v[60:63]
	v_mfma_f32_16x16x32_bf16 v[56:59], v[142:145], v[180:183], v[56:59]
	v_mfma_f32_16x16x32_bf16 v[44:47], v[126:129], v[190:193], v[44:47]
	v_mfma_f32_16x16x32_bf16 v[40:43], v[142:145], v[190:193], v[40:43]
	v_mfma_f32_16x16x32_bf16 v[28:31], v[126:129], v[198:201], v[28:31]
	v_mfma_f32_16x16x32_bf16 v[24:27], v[142:145], v[198:201], v[24:27]
	v_mfma_f32_16x16x32_bf16 v[12:15], v[126:129], v[206:209], v[12:15]
	v_mfma_f32_16x16x32_bf16 v[8:11], v[142:145], v[206:209], v[8:11]
	s_setprio 0
	s_setprio 1
	v_mfma_f32_16x16x32_bf16 v[52:55], v[146:149], v[174:177], v[52:55]
	v_mfma_f32_16x16x32_bf16 v[48:51], v[154:157], v[174:177], v[48:51]
	v_mfma_f32_16x16x32_bf16 v[36:39], v[146:149], v[184:187], v[36:39]
	v_mfma_f32_16x16x32_bf16 v[32:35], v[154:157], v[184:187], v[32:35]
	v_mfma_f32_16x16x32_bf16 v[20:23], v[146:149], v[194:197], v[20:23]
	v_mfma_f32_16x16x32_bf16 v[16:19], v[154:157], v[194:197], v[16:19]
	v_mfma_f32_16x16x32_bf16 v[4:7], v[146:149], v[202:205], v[4:7]
	v_mfma_f32_16x16x32_bf16 v[0:3], v[154:157], v[202:205], v[0:3]
	v_mfma_f32_16x16x32_bf16 v[52:55], v[150:153], v[180:183], v[52:55]
	v_mfma_f32_16x16x32_bf16 v[48:51], v[170:173], v[180:183], v[48:51]
	v_mfma_f32_16x16x32_bf16 v[36:39], v[150:153], v[190:193], v[36:39]
	v_mfma_f32_16x16x32_bf16 v[32:35], v[170:173], v[190:193], v[32:35]
	v_mfma_f32_16x16x32_bf16 v[20:23], v[150:153], v[198:201], v[20:23]
	v_mfma_f32_16x16x32_bf16 v[16:19], v[170:173], v[198:201], v[16:19]
	v_mfma_f32_16x16x32_bf16 v[4:7], v[150:153], v[206:209], v[4:7]
	v_mfma_f32_16x16x32_bf16 v[0:3], v[170:173], v[206:209], v[0:3]
	s_setprio 0
	s_barrier
	s_add_i32 s18, 0, 0x18000
	s_add_i32 s38, 0, 0x1c000
	v_add_u32_e32 v142, s18, v97
	v_add_u32_e32 v170, s38, v97
	ds_read_b128 v[122:125], v142
	ds_read_b128 v[126:129], v142 offset:1024
	ds_read_b128 v[138:141], v142 offset:2048
	ds_read_b128 v[142:145], v142 offset:3072
	ds_read_b128 v[146:149], v170
	ds_read_b128 v[150:153], v170 offset:1024
	ds_read_b128 v[154:157], v170 offset:2048
	ds_read_b128 v[170:173], v170 offset:3072
	s_add_u32 s2, s42, s98
	s_addc_u32 s3, s43, 0
	s_mov_b32 m0, s23
	v_lshl_add_u64 v[216:217], s[2:3], 0, v[164:165]
	ds_read_b128 v[174:177], v188 offset:32768
	ds_read_b128 v[180:183], v188 offset:33792
	ds_read_b128 v[184:187], v188 offset:34816
	ds_read_b128 v[190:193], v188 offset:35840
	ds_read_b128 v[194:197], v188 offset:36864
	ds_read_b128 v[198:201], v188 offset:37888
	ds_read_b128 v[202:205], v188 offset:38912
	ds_read_b128 v[206:209], v188 offset:39936
	global_load_lds_dwordx4 v[216:217], off
	v_lshl_add_u64 v[216:217], s[2:3], 0, v[160:161]
	s_mov_b32 m0, s19
	s_nop 0
	global_load_lds_dwordx4 v[216:217], off
	s_sleep 2
	s_waitcnt vmcnt(8)
	s_waitcnt lgkmcnt(0)
	s_barrier
	s_setprio 1
	s_waitcnt lgkmcnt(0)
	v_mfma_f32_16x16x32_bf16 v[134:137], v[122:125], v[174:177], v[134:137]
	v_mfma_f32_16x16x32_bf16 v[130:133], v[138:141], v[174:177], v[130:133]
	v_mfma_f32_16x16x32_bf16 v[110:113], v[122:125], v[184:187], v[110:113]
	v_mfma_f32_16x16x32_bf16 v[106:109], v[138:141], v[184:187], v[106:109]
	v_mfma_f32_16x16x32_bf16 v[92:95], v[122:125], v[194:197], v[92:95]
	v_mfma_f32_16x16x32_bf16 v[88:91], v[138:141], v[194:197], v[88:91]
	v_mfma_f32_16x16x32_bf16 v[76:79], v[122:125], v[202:205], v[76:79]
	v_mfma_f32_16x16x32_bf16 v[72:75], v[138:141], v[202:205], v[72:75]
	v_mfma_f32_16x16x32_bf16 v[134:137], v[126:129], v[180:183], v[134:137]
	v_mfma_f32_16x16x32_bf16 v[130:133], v[142:145], v[180:183], v[130:133]
	v_mfma_f32_16x16x32_bf16 v[110:113], v[126:129], v[190:193], v[110:113]
	v_mfma_f32_16x16x32_bf16 v[106:109], v[142:145], v[190:193], v[106:109]
	v_mfma_f32_16x16x32_bf16 v[92:95], v[126:129], v[198:201], v[92:95]
	v_mfma_f32_16x16x32_bf16 v[88:91], v[142:145], v[198:201], v[88:91]
	v_mfma_f32_16x16x32_bf16 v[76:79], v[126:129], v[206:209], v[76:79]
	v_mfma_f32_16x16x32_bf16 v[72:75], v[142:145], v[206:209], v[72:75]
	s_setprio 0
	s_setprio 1
	v_mfma_f32_16x16x32_bf16 v[118:121], v[146:149], v[174:177], v[118:121]
	v_mfma_f32_16x16x32_bf16 v[114:117], v[154:157], v[174:177], v[114:117]
	v_mfma_f32_16x16x32_bf16 v[102:105], v[146:149], v[184:187], v[102:105]
	v_mfma_f32_16x16x32_bf16 v[98:101], v[154:157], v[184:187], v[98:101]
	v_mfma_f32_16x16x32_bf16 v[84:87], v[146:149], v[194:197], v[84:87]
	v_mfma_f32_16x16x32_bf16 v[80:83], v[154:157], v[194:197], v[80:83]
	v_mfma_f32_16x16x32_bf16 v[68:71], v[146:149], v[202:205], v[68:71]
	v_mfma_f32_16x16x32_bf16 v[64:67], v[154:157], v[202:205], v[64:67]
	v_mfma_f32_16x16x32_bf16 v[118:121], v[150:153], v[180:183], v[118:121]
	v_mfma_f32_16x16x32_bf16 v[114:117], v[170:173], v[180:183], v[114:117]
	v_mfma_f32_16x16x32_bf16 v[102:105], v[150:153], v[190:193], v[102:105]
	v_mfma_f32_16x16x32_bf16 v[98:101], v[170:173], v[190:193], v[98:101]
	v_mfma_f32_16x16x32_bf16 v[84:87], v[150:153], v[198:201], v[84:87]
	v_mfma_f32_16x16x32_bf16 v[80:83], v[170:173], v[198:201], v[80:83]
	v_mfma_f32_16x16x32_bf16 v[68:71], v[150:153], v[206:209], v[68:71]
	v_mfma_f32_16x16x32_bf16 v[64:67], v[170:173], v[206:209], v[64:67]
	s_setprio 0
	s_barrier
; template <class Epi, class Sched, bool ALIGN_EPI = false, bool SP2 = false>
; __device__ __forceinline__ void gemm_phase(PG8_LAS unsigned char* lds, const Gemm g, const Sched& S, const Epi& E) {
;     ...
;         for (int t = (Epi::PEEL ? 2 : 0); t < nt; t += 2) {
;             const bool last = (t == nt - 2);
;             const char* a1 = cA + (size_t)(t + 1) * kstepA;
;             const char* a2 = last ? nA : cA + (size_t)(t + 2) * kstepA; const char* b2 = last ? nB : cB + (size_t)(t + 2) * kstepB;
;             const char* a3 = a2 + kstepA; const char* b3 = b2 + kstepB;
;             PG8_ITER(8);
;         }
	s_add_i32 s2, s18, s96
	v_lshl_add_u64 v[178:179], v[178:179], 0, s[36:37]
	s_mov_b32 m0, s2
	ds_read_b128 v[174:177], v188 offset:49152
	ds_read_b128 v[180:183], v188 offset:50176
	ds_read_b128 v[184:187], v188 offset:51200
	ds_read_b128 v[190:193], v188 offset:52224
	ds_read_b128 v[194:197], v188 offset:53248
	ds_read_b128 v[198:201], v188 offset:54272
	ds_read_b128 v[202:205], v188 offset:55296
	ds_read_b128 v[206:209], v188 offset:56320
	global_load_lds_dwordx4 v[178:179], off
	v_lshl_add_u64 v[178:179], v[210:211], 0, s[36:37]
	s_add_i32 m0, s2, 0x2000
	s_add_i32 s2, s38, s96
	global_load_lds_dwordx4 v[178:179], off
	v_lshl_add_u64 v[178:179], v[212:213], 0, s[36:37]
	s_mov_b32 m0, s2
	s_nop 0
	global_load_lds_dwordx4 v[178:179], off
	v_lshl_add_u64 v[178:179], v[214:215], 0, s[36:37]
	s_add_i32 m0, s2, 0x2000
	s_nop 0
	global_load_lds_dwordx4 v[178:179], off
	v_lshl_add_u64 v[178:179], s[44:45], 0, v[164:165]
	s_mov_b32 m0, s6
	s_nop 0
	global_load_lds_dwordx4 v[178:179], off
	v_lshl_add_u64 v[178:179], s[44:45], 0, v[160:161]
	s_mov_b32 m0, s56
	s_nop 0
	global_load_lds_dwordx4 v[178:179], off
	s_sleep 2
	s_waitcnt vmcnt(8)
	s_waitcnt lgkmcnt(0)
	s_barrier
	s_setprio 1
	s_waitcnt lgkmcnt(0)
	v_mfma_f32_16x16x32_bf16 v[60:63], v[122:125], v[174:177], v[60:63]
	v_mfma_f32_16x16x32_bf16 v[56:59], v[138:141], v[174:177], v[56:59]
	v_mfma_f32_16x16x32_bf16 v[44:47], v[122:125], v[184:187], v[44:47]
	v_mfma_f32_16x16x32_bf16 v[40:43], v[138:141], v[184:187], v[40:43]
	v_mfma_f32_16x16x32_bf16 v[28:31], v[122:125], v[194:197], v[28:31]
	v_mfma_f32_16x16x32_bf16 v[24:27], v[138:141], v[194:197], v[24:27]
	v_mfma_f32_16x16x32_bf16 v[12:15], v[122:125], v[202:205], v[12:15]
	v_mfma_f32_16x16x32_bf16 v[8:11], v[138:141], v[202:205], v[8:11]
	v_mfma_f32_16x16x32_bf16 v[60:63], v[126:129], v[180:183], v[60:63]
	v_mfma_f32_16x16x32_bf16 v[56:59], v[142:145], v[180:183], v[56:59]
	v_mfma_f32_16x16x32_bf16 v[44:47], v[126:129], v[190:193], v[44:47]
	v_mfma_f32_16x16x32_bf16 v[40:43], v[142:145], v[190:193], v[40:43]
	v_mfma_f32_16x16x32_bf16 v[28:31], v[126:129], v[198:201], v[28:31]
	v_mfma_f32_16x16x32_bf16 v[24:27], v[142:145], v[198:201], v[24:27]
	v_mfma_f32_16x16x32_bf16 v[12:15], v[126:129], v[206:209], v[12:15]
	v_mfma_f32_16x16x32_bf16 v[8:11], v[142:145], v[206:209], v[8:11]
	s_setprio 0
	s_setprio 1
	v_mfma_f32_16x16x32_bf16 v[52:55], v[146:149], v[174:177], v[52:55]
	v_mfma_f32_16x16x32_bf16 v[48:51], v[154:157], v[174:177], v[48:51]
	v_mfma_f32_16x16x32_bf16 v[36:39], v[146:149], v[184:187], v[36:39]
	v_mfma_f32_16x16x32_bf16 v[32:35], v[154:157], v[184:187], v[32:35]
	v_mfma_f32_16x16x32_bf16 v[20:23], v[146:149], v[194:197], v[20:23]
	v_mfma_f32_16x16x32_bf16 v[16:19], v[154:157], v[194:197], v[16:19]
	v_mfma_f32_16x16x32_bf16 v[4:7], v[146:149], v[202:205], v[4:7]
	v_mfma_f32_16x16x32_bf16 v[0:3], v[154:157], v[202:205], v[0:3]
	v_mfma_f32_16x16x32_bf16 v[52:55], v[150:153], v[180:183], v[52:55]
	v_mfma_f32_16x16x32_bf16 v[48:51], v[170:173], v[180:183], v[48:51]
	v_mfma_f32_16x16x32_bf16 v[36:39], v[150:153], v[190:193], v[36:39]
	v_mfma_f32_16x16x32_bf16 v[32:35], v[170:173], v[190:193], v[32:35]
	v_mfma_f32_16x16x32_bf16 v[20:23], v[150:153], v[198:201], v[20:23]
	v_mfma_f32_16x16x32_bf16 v[16:19], v[170:173], v[198:201], v[16:19]
	v_mfma_f32_16x16x32_bf16 v[4:7], v[150:153], v[206:209], v[4:7]
	v_mfma_f32_16x16x32_bf16 v[0:3], v[170:173], v[206:209], v[0:3]
	s_setprio 0
	s_barrier
	s_add_u32 s58, s58, 0x100
	s_addc_u32 s59, s59, 0
	s_add_u32 s24, s24, s49
	s_addc_u32 s25, s25, 0
	s_cmp_ge_u32 s10, s8
	s_cbranch_scc1 .LBB0_348
